# cross-attention unit v2: K staged in a 128-byte XOR-swizzled LDS image, fragment prefetch carried across S/softmax/PV phase boundaries, quarter-row reductions by permlane swaps instead of ds_bpermute
# baseline (speedup 1.0000x reference)
.LBB0_266:
	s_and_b64 vcc, exec, s[12:13]
	s_cbranch_vccz .LBB0_293
	v_readlane_b32 s10, v253, 7
	v_mov_b32_e32 v76, v241
	v_readlane_b32 s11, v253, 8
	s_and_b64 vcc, exec, s[10:11]
	v_readfirstlane_b32 s6, v76
	s_cbranch_vccz .LBB0_270
	s_and_b64 s[8:9], s[8:9], exec
	s_movk_i32 s8, 0x700
	s_cselect_b32 s10, s8, 0x400
	s_movk_i32 s8, 0xc00
	s_cselect_b32 s8, s8, 0x600
	s_add_u32 s8, s72, s8
	v_readlane_b32 s12, v254, 58
	s_addc_u32 s9, s73, 0
	v_readlane_b32 s13, v254, 59
	s_and_b64 s[12:13], s[12:13], exec
	s_cselect_b32 s11, 0x80000, 0
	v_readlane_b32 s12, v252, 53
	s_add_u32 s12, s12, s11
	v_readlane_b32 s13, v252, 54
	s_addc_u32 s13, s13, 0
	v_readlane_b32 s14, v252, 55
	s_add_u32 s14, s14, s11
	v_readlane_b32 s11, v252, 56
	v_lshlrev_b32_e32 v2, 4, v76
	s_addc_u32 s15, s11, 0
	v_and_b32_e32 v0, 0x70, v2
	v_mov_b32_e32 v1, v185
	v_lshl_add_u64 v[64:65], s[14:15], 0, v[0:1]
	v_add_u32_e32 v1, 0x200, v76
	v_ashrrev_i32_e32 v79, 3, v1
	v_ashrrev_i32_e32 v80, 5, v1
	v_add_u32_e32 v1, 0x400, v76
	v_ashrrev_i32_e32 v81, 3, v1
	v_ashrrev_i32_e32 v82, 5, v1
	v_add_u32_e32 v1, 0x600, v76
	v_and_b32_e32 v15, 64, v243
	v_ashrrev_i32_e32 v83, 3, v1
	v_ashrrev_i32_e32 v84, 5, v1
	v_add_u32_e32 v1, 0, v0
	v_xor_b32_e32 v0, 16, v243
	v_add_u32_e32 v15, 64, v15
	v_cmp_lt_i32_e32 vcc, v0, v15
	s_ashr_i32 s6, s6, 1
	v_and_b32_e32 v4, 63, v76
	v_cndmask_b32_e32 v0, v243, v0, vcc
	v_lshlrev_b32_e32 v85, 2, v0
	v_xor_b32_e32 v0, 32, v243
	v_and_b32_e32 v5, 15, v76
	s_andn2_b32 s6, s6, 31
	v_and_b32_e32 v184, 48, v76
	v_cmp_lt_i32_e32 vcc, v0, v15
	v_bfe_u32 v6, v76, 4, 2
	s_ashr_i32 s11, s6, 31
	v_or_b32_e32 v60, s6, v5
	v_lshl_add_u64 v[62:63], s[8:9], 0, v[184:185]
	v_and_b32_e32 v2, 0x1f0, v2
	v_mov_b32_e32 v3, v185
	v_ashrrev_i32_e32 v77, 3, v76
	v_ashrrev_i32_e32 v78, 5, v76
	s_movk_i32 s6, 0x90
	s_movk_i32 s8, 0x210
	v_cndmask_b32_e32 v0, v243, v0, vcc
	v_or_b32_e32 v16, 48, v4
	v_or_b32_e32 v18, 0x70, v4
	v_or_b32_e32 v19, 0xb0, v4
	v_or_b32_e32 v4, 0xf0, v4
	v_lshl_add_u64 v[66:67], s[12:13], 0, v[2:3]
	v_add_u32_e32 v2, 0, v2
	v_mul_lo_u32 v3, v77, s6
	v_mul_lo_u32 v7, v78, s8
	v_mul_lo_u32 v8, v79, s6
	v_mul_lo_u32 v9, v80, s8
	v_mul_lo_u32 v10, v81, s6
	v_mul_lo_u32 v11, v82, s8
	v_mul_lo_u32 v12, v83, s6
	v_mul_lo_u32 v13, v84, s8
	v_add_u32_e32 v14, 0, v184
	v_lshlrev_b32_e32 v86, 2, v0
	v_lshl_add_u32 v15, v6, 3, 0
	v_lshlrev_b32_e32 v0, 2, v6
	v_mul_u32_u24_e32 v6, 0x90, v5
	v_mul_u32_u24_e32 v17, 0x90, v16
	v_mul_u32_u24_e32 v18, 0x90, v18
	v_mul_u32_u24_e32 v19, 0x90, v19
	v_mul_u32_u24_e32 v4, 0x90, v4
	v_mul_u32_u24_e32 v5, 0x210, v5
	v_mul_u32_u24_e32 v16, 0x210, v16
	v_mov_b32_e32 v61, s11
	v_add_u32_e32 v87, v1, v3
	v_add_u32_e32 v88, v2, v7
	v_add_u32_e32 v89, v1, v8
	v_add_u32_e32 v90, v2, v9
	v_add_u32_e32 v91, v1, v10
	v_add_u32_e32 v92, v2, v11
	v_add_u32_e32 v93, v1, v12
	v_add_u32_e32 v94, v2, v13
	v_add_u32_e32 v95, v14, v6
	v_add_u32_e32 v96, v14, v17
	v_add_u32_e32 v97, v14, v18
	v_add_u32_e32 v98, v14, v19
	v_add_u32_e32 v99, v14, v4
	v_add_u32_e32 v100, v15, v5
	v_add_u32_e32 v101, v15, v16
	v_lshlrev_b32_e32 v184, 1, v0
	v_readlane_b32 s11, v252, 33
	s_mov_b32 s12, s87
	s_cmp_eq_u32 s100, 1
	s_cbranch_scc0 .Latt_nomap
	v_readlane_b32 s6, v252, 0
	s_nop 0
	s_and_b32 s8, s6, 7
	s_lshr_b32 s6, s6, 3
	s_lshr_b32 s13, s8, 1
	s_lshl_b32 s13, s13, 2
	s_lshr_b32 s14, s6, 3
	s_add_i32 s13, s13, s14
	s_lshl_b32 s13, s13, 4
	s_and_b32 s14, s8, 1
	s_lshl_b32 s14, s14, 3
	s_and_b32 s6, s6, 7
	s_add_i32 s14, s14, s6
	s_add_i32 s12, s13, s14
	s_lshl_b32 s11, s12, 9
	s_lshr_b32 s6, s12, 6
	s_bfe_u32 s8, s12, 0x20004
	s_and_b32 s9, s12, 15
	s_lshl_b32 s13, s6, 13
	s_lshl_b32 s14, s9, 9
	s_add_i32 s13, s13, s14
	v_readlane_b32 s14, v254, 58
	v_readlane_b32 s16, v252, 45
	v_readlane_b32 s17, v252, 46
	s_lshl_b32 s70, s8, 7
	s_cmp_lg_u32 s14, 0
	s_cselect_b32 s11, 1, 0
	v_lshrrev_b32_e32 v38, 3, v241
	v_and_b32_e32 v39, 7, v241
	v_lshlrev_b32_e32 v40, 9, v38
	v_lshl_add_u32 v40, v39, 4, v40
	v_bfe_u32 v41, v241, 4, 3
	v_xor_b32_e32 v41, v41, v39
	v_lshlrev_b32_e32 v41, 4, v41
	v_lshl_add_u32 v41, v38, 7, v41
	v_lshrrev_b32_e32 v38, 5, v241
	v_and_b32_e32 v39, 31, v241
	v_lshlrev_b32_e32 v42, 11, v38
	v_lshl_add_u32 v42, v39, 4, v42
	v_mul_u32_u24_e32 v43, 0x210, v38
	v_lshl_add_u32 v43, v39, 4, v43
	s_lshl_b32 s14, s11, 19
	s_add_i32 s14, s14, 0x100000
	s_lshl_b32 s15, s6, 17
	s_add_i32 s14, s14, s15
	s_add_i32 s14, s14, s70
	s_add_u32 s14, s16, s14
	s_addc_u32 s15, s17, 0
	s_lshl_b32 s8, s11, 19
	s_add_i32 s8, s8, 0x200000
	s_lshl_b32 s9, s70, 10
	s_add_i32 s8, s8, s9
	s_lshl_b32 s9, s6, 9
	s_add_i32 s8, s8, s9
	s_add_u32 s8, s16, s8
	s_addc_u32 s9, s17, 0
	global_load_dwordx4 v[78:81], v40, s[14:15]
	global_load_dwordx4 v[94:97], v42, s[8:9]
	s_add_u32 s14, s14, 0x8000
	s_addc_u32 s15, s15, 0
	s_add_u32 s8, s8, 0x8000
	s_addc_u32 s9, s9, 0
	global_load_dwordx4 v[82:85], v40, s[14:15]
	global_load_dwordx4 v[98:101], v42, s[8:9]
	s_add_u32 s14, s14, 0x8000
	s_addc_u32 s15, s15, 0
	s_add_u32 s8, s8, 0x8000
	s_addc_u32 s9, s9, 0
	global_load_dwordx4 v[86:89], v40, s[14:15]
	global_load_dwordx4 v[102:105], v42, s[8:9]
	s_add_u32 s14, s14, 0x8000
	s_addc_u32 s15, s15, 0
	s_add_u32 s8, s8, 0x8000
	s_addc_u32 s9, s9, 0
	global_load_dwordx4 v[90:93], v40, s[14:15]
	global_load_dwordx4 v[106:109], v42, s[8:9]
	v_and_b32_e32 v32, 63, v241
	v_and_b32_e32 v33, 15, v32
	v_lshrrev_b32_e32 v34, 4, v32
	v_lshrrev_b32_e32 v35, 6, v241
	v_lshl_add_u32 v36, v35, 5, v33
	s_cmp_eq_u32 s11, 1
	s_movk_i32 s6, 0xe00
	s_cselect_b32 s6, 0x800, s6
	s_movk_i32 s14, 0xc00
	s_cselect_b32 s14, 0x600, s14
	s_mul_i32 s12, s13, s6
	s_add_i32 s12, s12, s14
	s_add_i32 s12, s12, s70
	s_add_u32 s12, s12, 0xd800000
	s_add_u32 s8, s16, s12
	s_addc_u32 s9, s17, 0
	v_mul_lo_u32 v37, v36, s6
	v_lshl_add_u32 v37, v34, 4, v37
	s_mul_i32 s12, s6, 0
	s_add_u32 s14, s8, s12
	s_addc_u32 s15, s9, 0
	global_load_dwordx4 v[0:3], v37, s[14:15]
	global_load_dwordx4 v[4:7], v37, s[14:15] offset:64
	s_mul_i32 s12, s6, 16
	s_add_u32 s14, s8, s12
	s_addc_u32 s15, s9, 0
	global_load_dwordx4 v[8:11], v37, s[14:15]
	global_load_dwordx4 v[12:15], v37, s[14:15] offset:64
	s_mul_i32 s12, s6, 256
	s_add_u32 s14, s8, s12
	s_addc_u32 s15, s9, 0
	global_load_dwordx4 v[16:19], v37, s[14:15]
	global_load_dwordx4 v[20:23], v37, s[14:15] offset:64
	s_mul_i32 s12, s6, 272
	s_add_u32 s14, s8, s12
	s_addc_u32 s15, s9, 0
	global_load_dwordx4 v[24:27], v37, s[14:15]
	global_load_dwordx4 v[28:31], v37, s[14:15] offset:64
	s_lshl_b32 s12, s13, 11
	s_add_i32 s12, s12, s70
	s_add_u32 s12, s12, 0x9800600
	s_add_u32 s12, s16, s12
	s_addc_u32 s13, s17, 0
	v_bfe_u32 v44, v33, 1, 2
	v_xor_b32_e32 v44, v44, v34
	v_lshrrev_b32_e32 v45, 3, v33
	v_lshl_add_u32 v46, v45, 2, v44
	v_xor_b32_e32 v45, 1, v45
	v_lshl_add_u32 v47, v45, 2, v44
	v_lshlrev_b32_e32 v72, 7, v33
	v_lshl_add_u32 v146, v47, 4, v72
	v_lshl_add_u32 v72, v46, 4, v72
	v_mul_u32_u24_e32 v73, 0x210, v33
	v_lshl_add_u32 v73, v34, 3, v73
	v_lshlrev_b32_e32 v74, 11, v36
	v_lshl_add_u32 v74, v34, 3, v74
	v_mov_b32_e32 v144, 0x3e38aa3b
	v_mov_b32_e32 v145, 0x3e38aa3b
	s_waitcnt vmcnt(8)
	ds_write_b128 v41, v[78:81] offset:0
	ds_write_b128 v43, v[94:97] offset:36864
	ds_write_b128 v41, v[82:85] offset:8192
	ds_write_b128 v43, v[98:101] offset:45312
	ds_write_b128 v41, v[86:89] offset:16384
	ds_write_b128 v43, v[102:105] offset:53760
	ds_write_b128 v41, v[90:93] offset:24576
	ds_write_b128 v43, v[106:109] offset:62208
	s_waitcnt vmcnt(0) lgkmcnt(0)
	s_barrier
	ds_read_b128 v[48:51], v72 offset:0
	ds_read_b128 v[52:55], v146 offset:0
	ds_read_b128 v[56:59], v72 offset:2048
	ds_read_b128 v[60:63], v146 offset:2048
	ds_read_b128 v[64:67], v72 offset:4096
	ds_read_b128 v[68:71], v146 offset:4096
	ds_read_b128 v[32:35], v72 offset:6144
	ds_read_b128 v[36:39], v146 offset:6144
	ds_read_b128 v[40:43], v72 offset:8192
	s_waitcnt lgkmcnt(8)
	v_mfma_f32_16x16x32_bf16 v[78:81], v[48:51], v[0:3], 0
	ds_read_b128 v[44:47], v146 offset:8192
	s_waitcnt lgkmcnt(8)
	v_mfma_f32_16x16x32_bf16 v[78:81], v[52:55], v[4:7], v[78:81]
	ds_read_b128 v[48:51], v72 offset:10240
	s_waitcnt lgkmcnt(8)
	v_mfma_f32_16x16x32_bf16 v[82:85], v[56:59], v[0:3], 0
	ds_read_b128 v[52:55], v146 offset:10240
	s_waitcnt lgkmcnt(8)
	v_mfma_f32_16x16x32_bf16 v[82:85], v[60:63], v[4:7], v[82:85]
	ds_read_b128 v[56:59], v72 offset:12288
	s_waitcnt lgkmcnt(8)
	v_mfma_f32_16x16x32_bf16 v[86:89], v[64:67], v[0:3], 0
	ds_read_b128 v[60:63], v146 offset:12288
	s_waitcnt lgkmcnt(8)
	v_mfma_f32_16x16x32_bf16 v[86:89], v[68:71], v[4:7], v[86:89]
	ds_read_b128 v[64:67], v72 offset:14336
	s_waitcnt lgkmcnt(8)
	v_mfma_f32_16x16x32_bf16 v[90:93], v[32:35], v[0:3], 0
	ds_read_b128 v[68:71], v146 offset:14336
	s_waitcnt lgkmcnt(8)
	v_mfma_f32_16x16x32_bf16 v[90:93], v[36:39], v[4:7], v[90:93]
	ds_read_b128 v[32:35], v72 offset:16384
	s_waitcnt lgkmcnt(8)
	v_mfma_f32_16x16x32_bf16 v[94:97], v[40:43], v[0:3], 0
	ds_read_b128 v[36:39], v146 offset:16384
	s_waitcnt lgkmcnt(8)
	v_mfma_f32_16x16x32_bf16 v[94:97], v[44:47], v[4:7], v[94:97]
	ds_read_b128 v[40:43], v72 offset:18432
	s_waitcnt lgkmcnt(8)
	v_mfma_f32_16x16x32_bf16 v[98:101], v[48:51], v[0:3], 0
	ds_read_b128 v[44:47], v146 offset:18432
	s_waitcnt lgkmcnt(8)
	v_mfma_f32_16x16x32_bf16 v[98:101], v[52:55], v[4:7], v[98:101]
	ds_read_b128 v[48:51], v72 offset:20480
	s_waitcnt lgkmcnt(8)
	v_mfma_f32_16x16x32_bf16 v[102:105], v[56:59], v[0:3], 0
	ds_read_b128 v[52:55], v146 offset:20480
	s_waitcnt lgkmcnt(8)
	v_mfma_f32_16x16x32_bf16 v[102:105], v[60:63], v[4:7], v[102:105]
	ds_read_b128 v[56:59], v72 offset:22528
	s_waitcnt lgkmcnt(8)
	v_mfma_f32_16x16x32_bf16 v[106:109], v[64:67], v[0:3], 0
	ds_read_b128 v[60:63], v146 offset:22528
	s_waitcnt lgkmcnt(8)
	v_mfma_f32_16x16x32_bf16 v[106:109], v[68:71], v[4:7], v[106:109]
	ds_read_b128 v[64:67], v72 offset:24576
	s_waitcnt lgkmcnt(8)
	v_mfma_f32_16x16x32_bf16 v[110:113], v[32:35], v[0:3], 0
	ds_read_b128 v[68:71], v146 offset:24576
	s_waitcnt lgkmcnt(8)
	v_mfma_f32_16x16x32_bf16 v[110:113], v[36:39], v[4:7], v[110:113]
	ds_read_b128 v[32:35], v72 offset:26624
	s_waitcnt lgkmcnt(8)
	v_mfma_f32_16x16x32_bf16 v[114:117], v[40:43], v[0:3], 0
	ds_read_b128 v[36:39], v146 offset:26624
	s_waitcnt lgkmcnt(8)
	v_mfma_f32_16x16x32_bf16 v[114:117], v[44:47], v[4:7], v[114:117]
	ds_read_b128 v[40:43], v72 offset:28672
	s_waitcnt lgkmcnt(8)
	v_mfma_f32_16x16x32_bf16 v[118:121], v[48:51], v[0:3], 0
	ds_read_b128 v[44:47], v146 offset:28672
	s_waitcnt lgkmcnt(8)
	v_mfma_f32_16x16x32_bf16 v[118:121], v[52:55], v[4:7], v[118:121]
	ds_read_b128 v[48:51], v72 offset:30720
	s_waitcnt lgkmcnt(8)
	v_mfma_f32_16x16x32_bf16 v[122:125], v[56:59], v[0:3], 0
	ds_read_b128 v[52:55], v146 offset:30720
	s_waitcnt lgkmcnt(8)
	v_mfma_f32_16x16x32_bf16 v[122:125], v[60:63], v[4:7], v[122:125]
	s_waitcnt lgkmcnt(7)
	v_mfma_f32_16x16x32_bf16 v[126:129], v[64:67], v[0:3], 0
	s_waitcnt lgkmcnt(6)
	v_mfma_f32_16x16x32_bf16 v[126:129], v[68:71], v[4:7], v[126:129]
	s_waitcnt lgkmcnt(5)
	v_mfma_f32_16x16x32_bf16 v[130:133], v[32:35], v[0:3], 0
	s_waitcnt lgkmcnt(4)
	v_mfma_f32_16x16x32_bf16 v[130:133], v[36:39], v[4:7], v[130:133]
	s_waitcnt lgkmcnt(3)
	v_mfma_f32_16x16x32_bf16 v[134:137], v[40:43], v[0:3], 0
	s_waitcnt lgkmcnt(2)
	v_mfma_f32_16x16x32_bf16 v[134:137], v[44:47], v[4:7], v[134:137]
	s_waitcnt lgkmcnt(1)
	v_mfma_f32_16x16x32_bf16 v[138:141], v[48:51], v[0:3], 0
	s_waitcnt lgkmcnt(0)
	v_mfma_f32_16x16x32_bf16 v[138:141], v[52:55], v[4:7], v[138:141]
	ds_read_b64 v[48:49], v73 offset:36864
	ds_read_b64 v[50:51], v73 offset:36896
	ds_read_b64 v[52:53], v73 offset:45312
	ds_read_b64 v[54:55], v73 offset:45344
	ds_read_b64 v[56:57], v73 offset:53760
	ds_read_b64 v[58:59], v73 offset:53792
	ds_read_b64 v[60:61], v73 offset:62208
	ds_read_b64 v[62:63], v73 offset:62240
	ds_read_b64 v[64:65], v73 offset:36928
	ds_read_b64 v[66:67], v73 offset:36960
	ds_read_b64 v[68:69], v73 offset:45376
	ds_read_b64 v[70:71], v73 offset:45408
	v_max3_f32 v36, v78, v79, v80
	v_max3_f32 v36, v36, v81, v82
	v_max3_f32 v36, v36, v83, v84
	v_max3_f32 v36, v36, v85, v86
	v_max3_f32 v36, v36, v87, v88
	v_max3_f32 v36, v36, v89, v90
	v_max3_f32 v36, v36, v91, v92
	v_max3_f32 v36, v36, v93, v94
	v_max3_f32 v36, v36, v95, v96
	v_max3_f32 v36, v36, v97, v98
	v_max3_f32 v36, v36, v99, v100
	v_max3_f32 v36, v36, v101, v102
	v_max3_f32 v36, v36, v103, v104
	v_max3_f32 v36, v36, v105, v106
	v_max3_f32 v36, v36, v107, v108
	v_max3_f32 v36, v36, v109, v110
	v_max3_f32 v36, v36, v111, v112
	v_max3_f32 v36, v36, v113, v114
	v_max3_f32 v36, v36, v115, v116
	v_max3_f32 v36, v36, v117, v118
	v_max3_f32 v36, v36, v119, v120
	v_max3_f32 v36, v36, v121, v122
	v_max3_f32 v36, v36, v123, v124
	v_max3_f32 v36, v36, v125, v126
	v_max3_f32 v36, v36, v127, v128
	v_max3_f32 v36, v36, v129, v130
	v_max3_f32 v36, v36, v131, v132
	v_max3_f32 v36, v36, v133, v134
	v_max3_f32 v36, v36, v135, v136
	v_max3_f32 v36, v36, v137, v138
	v_max3_f32 v36, v36, v139, v140
	v_max_f32_e32 v36, v36, v141
	v_mov_b32_e32 v37, v36
	s_nop 1
	v_permlane16_swap_b32_e32 v36, v37
	v_max_f32_e32 v36, v36, v37
	v_mov_b32_e32 v37, v36
	s_nop 1
	v_permlane32_swap_b32_e32 v36, v37
	v_max_f32_e32 v36, v36, v37
	v_mul_f32_e64 v38, v36, -v144
	v_mov_b32_e32 v40, 0
	v_mov_b32_e32 v41, 0
	v_mov_b32_e32 v39, v38
	v_pk_fma_f32 v[78:79], v[78:79], v[144:145], v[38:39]
	v_pk_fma_f32 v[80:81], v[80:81], v[144:145], v[38:39]
	v_exp_f32_e32 v78, v78
	v_exp_f32_e32 v79, v79
	v_exp_f32_e32 v80, v80
	v_exp_f32_e32 v81, v81
	v_pk_fma_f32 v[82:83], v[82:83], v[144:145], v[38:39]
	v_pk_fma_f32 v[84:85], v[84:85], v[144:145], v[38:39]
	v_exp_f32_e32 v82, v82
	v_exp_f32_e32 v83, v83
	v_exp_f32_e32 v84, v84
	v_exp_f32_e32 v85, v85
	v_pk_add_f32 v[40:41], v[40:41], v[78:79]
	v_pk_add_f32 v[40:41], v[40:41], v[80:81]
	v_pk_fma_f32 v[86:87], v[86:87], v[144:145], v[38:39]
	v_pk_fma_f32 v[88:89], v[88:89], v[144:145], v[38:39]
	v_exp_f32_e32 v86, v86
	v_exp_f32_e32 v87, v87
	v_exp_f32_e32 v88, v88
	v_exp_f32_e32 v89, v89
	v_pk_add_f32 v[40:41], v[40:41], v[82:83]
	v_pk_add_f32 v[40:41], v[40:41], v[84:85]
	v_pk_fma_f32 v[90:91], v[90:91], v[144:145], v[38:39]
	v_pk_fma_f32 v[92:93], v[92:93], v[144:145], v[38:39]
	v_exp_f32_e32 v90, v90
	v_exp_f32_e32 v91, v91
	v_exp_f32_e32 v92, v92
	v_exp_f32_e32 v93, v93
	v_pk_add_f32 v[40:41], v[40:41], v[86:87]
	v_pk_add_f32 v[40:41], v[40:41], v[88:89]
	v_pk_fma_f32 v[94:95], v[94:95], v[144:145], v[38:39]
	v_pk_fma_f32 v[96:97], v[96:97], v[144:145], v[38:39]
	v_exp_f32_e32 v94, v94
	v_exp_f32_e32 v95, v95
	v_exp_f32_e32 v96, v96
	v_exp_f32_e32 v97, v97
	v_pk_add_f32 v[40:41], v[40:41], v[90:91]
	v_pk_add_f32 v[40:41], v[40:41], v[92:93]
	v_pk_fma_f32 v[98:99], v[98:99], v[144:145], v[38:39]
	v_pk_fma_f32 v[100:101], v[100:101], v[144:145], v[38:39]
	v_exp_f32_e32 v98, v98
	v_exp_f32_e32 v99, v99
	v_exp_f32_e32 v100, v100
	v_exp_f32_e32 v101, v101
	v_pk_add_f32 v[40:41], v[40:41], v[94:95]
	v_pk_add_f32 v[40:41], v[40:41], v[96:97]
	v_pk_fma_f32 v[102:103], v[102:103], v[144:145], v[38:39]
	v_pk_fma_f32 v[104:105], v[104:105], v[144:145], v[38:39]
	v_exp_f32_e32 v102, v102
	v_exp_f32_e32 v103, v103
	v_exp_f32_e32 v104, v104
	v_exp_f32_e32 v105, v105
	v_pk_add_f32 v[40:41], v[40:41], v[98:99]
	v_pk_add_f32 v[40:41], v[40:41], v[100:101]
	v_pk_fma_f32 v[106:107], v[106:107], v[144:145], v[38:39]
	v_pk_fma_f32 v[108:109], v[108:109], v[144:145], v[38:39]
	v_exp_f32_e32 v106, v106
	v_exp_f32_e32 v107, v107
	v_exp_f32_e32 v108, v108
	v_exp_f32_e32 v109, v109
	v_pk_add_f32 v[40:41], v[40:41], v[102:103]
	v_pk_add_f32 v[40:41], v[40:41], v[104:105]
	v_pk_fma_f32 v[110:111], v[110:111], v[144:145], v[38:39]
	v_pk_fma_f32 v[112:113], v[112:113], v[144:145], v[38:39]
	v_exp_f32_e32 v110, v110
	v_exp_f32_e32 v111, v111
	v_exp_f32_e32 v112, v112
	v_exp_f32_e32 v113, v113
	v_pk_add_f32 v[40:41], v[40:41], v[106:107]
	v_pk_add_f32 v[40:41], v[40:41], v[108:109]
	v_pk_fma_f32 v[114:115], v[114:115], v[144:145], v[38:39]
	v_pk_fma_f32 v[116:117], v[116:117], v[144:145], v[38:39]
	v_exp_f32_e32 v114, v114
	v_exp_f32_e32 v115, v115
	v_exp_f32_e32 v116, v116
	v_exp_f32_e32 v117, v117
	v_pk_add_f32 v[40:41], v[40:41], v[110:111]
	v_pk_add_f32 v[40:41], v[40:41], v[112:113]
	v_pk_fma_f32 v[118:119], v[118:119], v[144:145], v[38:39]
	v_pk_fma_f32 v[120:121], v[120:121], v[144:145], v[38:39]
	v_exp_f32_e32 v118, v118
	v_exp_f32_e32 v119, v119
	v_exp_f32_e32 v120, v120
	v_exp_f32_e32 v121, v121
	v_pk_add_f32 v[40:41], v[40:41], v[114:115]
	v_pk_add_f32 v[40:41], v[40:41], v[116:117]
	v_pk_fma_f32 v[122:123], v[122:123], v[144:145], v[38:39]
	v_pk_fma_f32 v[124:125], v[124:125], v[144:145], v[38:39]
	v_exp_f32_e32 v122, v122
	v_exp_f32_e32 v123, v123
	v_exp_f32_e32 v124, v124
	v_exp_f32_e32 v125, v125
	v_pk_add_f32 v[40:41], v[40:41], v[118:119]
	v_pk_add_f32 v[40:41], v[40:41], v[120:121]
	v_pk_fma_f32 v[126:127], v[126:127], v[144:145], v[38:39]
	v_pk_fma_f32 v[128:129], v[128:129], v[144:145], v[38:39]
	v_exp_f32_e32 v126, v126
	v_exp_f32_e32 v127, v127
	v_exp_f32_e32 v128, v128
	v_exp_f32_e32 v129, v129
	v_pk_add_f32 v[40:41], v[40:41], v[122:123]
	v_pk_add_f32 v[40:41], v[40:41], v[124:125]
	v_pk_fma_f32 v[130:131], v[130:131], v[144:145], v[38:39]
	v_pk_fma_f32 v[132:133], v[132:133], v[144:145], v[38:39]
	v_exp_f32_e32 v130, v130
	v_exp_f32_e32 v131, v131
	v_exp_f32_e32 v132, v132
	v_exp_f32_e32 v133, v133
	v_pk_add_f32 v[40:41], v[40:41], v[126:127]
	v_pk_add_f32 v[40:41], v[40:41], v[128:129]
	v_pk_fma_f32 v[134:135], v[134:135], v[144:145], v[38:39]
	v_pk_fma_f32 v[136:137], v[136:137], v[144:145], v[38:39]
	v_exp_f32_e32 v134, v134
	v_exp_f32_e32 v135, v135
	v_exp_f32_e32 v136, v136
	v_exp_f32_e32 v137, v137
	v_pk_add_f32 v[40:41], v[40:41], v[130:131]
	v_pk_add_f32 v[40:41], v[40:41], v[132:133]
	v_pk_fma_f32 v[138:139], v[138:139], v[144:145], v[38:39]
	v_pk_fma_f32 v[140:141], v[140:141], v[144:145], v[38:39]
	v_exp_f32_e32 v138, v138
	v_exp_f32_e32 v139, v139
	v_exp_f32_e32 v140, v140
	v_exp_f32_e32 v141, v141
	v_pk_add_f32 v[40:41], v[40:41], v[134:135]
	v_pk_add_f32 v[40:41], v[40:41], v[136:137]
	s_nop 0
	v_pk_add_f32 v[40:41], v[40:41], v[138:139]
	v_pk_add_f32 v[40:41], v[40:41], v[140:141]
	v_add_f32_e32 v36, v40, v41
	v_mov_b32_e32 v37, v36
	s_nop 1
	v_permlane16_swap_b32_e32 v36, v37
	v_add_f32_e32 v36, v36, v37
	v_mov_b32_e32 v37, v36
	s_nop 1
	v_permlane32_swap_b32_e32 v36, v37
	v_add_f32_e32 v36, v36, v37
	v_rcp_f32_e32 v142, v36
	v_cvt_pk_bf16_f32 v78, v78, v79
	v_cvt_pk_bf16_f32 v79, v80, v81
	v_cvt_pk_bf16_f32 v80, v82, v83
	v_cvt_pk_bf16_f32 v81, v84, v85
	v_cvt_pk_bf16_f32 v86, v86, v87
	v_cvt_pk_bf16_f32 v87, v88, v89
	v_cvt_pk_bf16_f32 v88, v90, v91
	v_cvt_pk_bf16_f32 v89, v92, v93
	v_cvt_pk_bf16_f32 v94, v94, v95
	v_cvt_pk_bf16_f32 v95, v96, v97
	v_cvt_pk_bf16_f32 v96, v98, v99
	v_cvt_pk_bf16_f32 v97, v100, v101
	v_cvt_pk_bf16_f32 v102, v102, v103
	v_cvt_pk_bf16_f32 v103, v104, v105
	v_cvt_pk_bf16_f32 v104, v106, v107
	v_cvt_pk_bf16_f32 v105, v108, v109
	v_cvt_pk_bf16_f32 v110, v110, v111
	v_cvt_pk_bf16_f32 v111, v112, v113
	v_cvt_pk_bf16_f32 v112, v114, v115
	v_cvt_pk_bf16_f32 v113, v116, v117
	v_cvt_pk_bf16_f32 v118, v118, v119
	v_cvt_pk_bf16_f32 v119, v120, v121
	v_cvt_pk_bf16_f32 v120, v122, v123
	v_cvt_pk_bf16_f32 v121, v124, v125
	v_cvt_pk_bf16_f32 v126, v126, v127
	v_cvt_pk_bf16_f32 v127, v128, v129
	v_cvt_pk_bf16_f32 v128, v130, v131
	v_cvt_pk_bf16_f32 v129, v132, v133
	v_cvt_pk_bf16_f32 v134, v134, v135
	v_cvt_pk_bf16_f32 v135, v136, v137
	v_cvt_pk_bf16_f32 v136, v138, v139
	v_cvt_pk_bf16_f32 v137, v140, v141
	v_fma_f32 v143, -v36, v142, 1.0
	v_fma_f32 v142, v143, v142, v142
	v_mov_b32_e32 v143, v142
	ds_read_b64 v[82:83], v73 offset:53824
	ds_read_b64 v[84:85], v73 offset:53856
	s_waitcnt lgkmcnt(12)
	v_mfma_f32_16x16x32_bf16 v[32:35], v[48:51], v[78:81], 0
	ds_read_b64 v[90:91], v73 offset:62272
	ds_read_b64 v[92:93], v73 offset:62304
	s_waitcnt lgkmcnt(12)
	v_mfma_f32_16x16x32_bf16 v[36:39], v[52:55], v[78:81], 0
	ds_read_b64 v[48:49], v73 offset:36992
	ds_read_b64 v[50:51], v73 offset:37024
	s_waitcnt lgkmcnt(12)
	v_mfma_f32_16x16x32_bf16 v[40:43], v[56:59], v[78:81], 0
	ds_read_b64 v[52:53], v73 offset:45440
	ds_read_b64 v[54:55], v73 offset:45472
	s_waitcnt lgkmcnt(12)
	v_mfma_f32_16x16x32_bf16 v[44:47], v[60:63], v[78:81], 0
	ds_read_b64 v[56:57], v73 offset:53888
	ds_read_b64 v[58:59], v73 offset:53920
	s_waitcnt lgkmcnt(12)
	v_mfma_f32_16x16x32_bf16 v[32:35], v[64:67], v[86:89], v[32:35]
	ds_read_b64 v[60:61], v73 offset:62336
	ds_read_b64 v[62:63], v73 offset:62368
	s_waitcnt lgkmcnt(12)
	v_mfma_f32_16x16x32_bf16 v[36:39], v[68:71], v[86:89], v[36:39]
	ds_read_b64 v[64:65], v73 offset:37056
	ds_read_b64 v[66:67], v73 offset:37088
	s_waitcnt lgkmcnt(12)
	v_mfma_f32_16x16x32_bf16 v[40:43], v[82:85], v[86:89], v[40:43]
	ds_read_b64 v[68:69], v73 offset:45504
	ds_read_b64 v[70:71], v73 offset:45536
	s_waitcnt lgkmcnt(12)
	v_mfma_f32_16x16x32_bf16 v[44:47], v[90:93], v[86:89], v[44:47]
	ds_read_b64 v[82:83], v73 offset:53952
	ds_read_b64 v[84:85], v73 offset:53984
	s_waitcnt lgkmcnt(12)
	v_mfma_f32_16x16x32_bf16 v[32:35], v[48:51], v[94:97], v[32:35]
	ds_read_b64 v[90:91], v73 offset:62400
	ds_read_b64 v[92:93], v73 offset:62432
	s_waitcnt lgkmcnt(12)
	v_mfma_f32_16x16x32_bf16 v[36:39], v[52:55], v[94:97], v[36:39]
	ds_read_b64 v[48:49], v73 offset:37120
	ds_read_b64 v[50:51], v73 offset:37152
	s_waitcnt lgkmcnt(12)
	v_mfma_f32_16x16x32_bf16 v[40:43], v[56:59], v[94:97], v[40:43]
	ds_read_b64 v[52:53], v73 offset:45568
	ds_read_b64 v[54:55], v73 offset:45600
	s_waitcnt lgkmcnt(12)
	v_mfma_f32_16x16x32_bf16 v[44:47], v[60:63], v[94:97], v[44:47]
	ds_read_b64 v[56:57], v73 offset:54016
	ds_read_b64 v[58:59], v73 offset:54048
	s_waitcnt lgkmcnt(12)
	v_mfma_f32_16x16x32_bf16 v[32:35], v[64:67], v[102:105], v[32:35]
	ds_read_b64 v[60:61], v73 offset:62464
	ds_read_b64 v[62:63], v73 offset:62496
	s_waitcnt lgkmcnt(12)
	v_mfma_f32_16x16x32_bf16 v[36:39], v[68:71], v[102:105], v[36:39]
	ds_read_b64 v[64:65], v73 offset:37184
	ds_read_b64 v[66:67], v73 offset:37216
	s_waitcnt lgkmcnt(12)
	v_mfma_f32_16x16x32_bf16 v[40:43], v[82:85], v[102:105], v[40:43]
	ds_read_b64 v[68:69], v73 offset:45632
	ds_read_b64 v[70:71], v73 offset:45664
	s_waitcnt lgkmcnt(12)
	v_mfma_f32_16x16x32_bf16 v[44:47], v[90:93], v[102:105], v[44:47]
	ds_read_b64 v[82:83], v73 offset:54080
	ds_read_b64 v[84:85], v73 offset:54112
	s_waitcnt lgkmcnt(12)
	v_mfma_f32_16x16x32_bf16 v[32:35], v[48:51], v[110:113], v[32:35]
	ds_read_b64 v[90:91], v73 offset:62528
	ds_read_b64 v[92:93], v73 offset:62560
	s_waitcnt lgkmcnt(12)
	v_mfma_f32_16x16x32_bf16 v[36:39], v[52:55], v[110:113], v[36:39]
	ds_read_b64 v[48:49], v73 offset:37248
	ds_read_b64 v[50:51], v73 offset:37280
	s_waitcnt lgkmcnt(12)
	v_mfma_f32_16x16x32_bf16 v[40:43], v[56:59], v[110:113], v[40:43]
	ds_read_b64 v[52:53], v73 offset:45696
	ds_read_b64 v[54:55], v73 offset:45728
	s_waitcnt lgkmcnt(12)
	v_mfma_f32_16x16x32_bf16 v[44:47], v[60:63], v[110:113], v[44:47]
	ds_read_b64 v[56:57], v73 offset:54144
	ds_read_b64 v[58:59], v73 offset:54176
	s_waitcnt lgkmcnt(12)
	v_mfma_f32_16x16x32_bf16 v[32:35], v[64:67], v[118:121], v[32:35]
	ds_read_b64 v[60:61], v73 offset:62592
	ds_read_b64 v[62:63], v73 offset:62624
	s_waitcnt lgkmcnt(12)
	v_mfma_f32_16x16x32_bf16 v[36:39], v[68:71], v[118:121], v[36:39]
	ds_read_b64 v[64:65], v73 offset:37312
	ds_read_b64 v[66:67], v73 offset:37344
	s_waitcnt lgkmcnt(12)
	v_mfma_f32_16x16x32_bf16 v[40:43], v[82:85], v[118:121], v[40:43]
	ds_read_b64 v[68:69], v73 offset:45760
	ds_read_b64 v[70:71], v73 offset:45792
	s_waitcnt lgkmcnt(12)
	v_mfma_f32_16x16x32_bf16 v[44:47], v[90:93], v[118:121], v[44:47]
	ds_read_b64 v[82:83], v73 offset:54208
	ds_read_b64 v[84:85], v73 offset:54240
	s_waitcnt lgkmcnt(12)
	v_mfma_f32_16x16x32_bf16 v[32:35], v[48:51], v[126:129], v[32:35]
	ds_read_b64 v[90:91], v73 offset:62656
	ds_read_b64 v[92:93], v73 offset:62688
	s_waitcnt lgkmcnt(12)
	v_mfma_f32_16x16x32_bf16 v[36:39], v[52:55], v[126:129], v[36:39]
	s_waitcnt lgkmcnt(10)
	v_mfma_f32_16x16x32_bf16 v[40:43], v[56:59], v[126:129], v[40:43]
	s_waitcnt lgkmcnt(8)
	v_mfma_f32_16x16x32_bf16 v[44:47], v[60:63], v[126:129], v[44:47]
	s_waitcnt lgkmcnt(6)
	v_mfma_f32_16x16x32_bf16 v[32:35], v[64:67], v[134:137], v[32:35]
	s_waitcnt lgkmcnt(4)
	v_mfma_f32_16x16x32_bf16 v[36:39], v[68:71], v[134:137], v[36:39]
	s_waitcnt lgkmcnt(2)
	v_mfma_f32_16x16x32_bf16 v[40:43], v[82:85], v[134:137], v[40:43]
	s_waitcnt lgkmcnt(0)
	v_mfma_f32_16x16x32_bf16 v[44:47], v[90:93], v[134:137], v[44:47]
	ds_read_b128 v[48:51], v72 offset:0
	ds_read_b128 v[52:55], v146 offset:0
	ds_read_b128 v[56:59], v72 offset:2048
	ds_read_b128 v[60:63], v146 offset:2048
	ds_read_b128 v[64:67], v72 offset:4096
	ds_read_b128 v[68:71], v146 offset:4096
	s_add_u32 s16, s12, 0x0
	s_addc_u32 s17, s13, 0
	s_nop 7
	v_pk_mul_f32 v[32:33], v[32:33], v[142:143]
	v_pk_mul_f32 v[34:35], v[34:35], v[142:143]
	v_pk_mul_f32 v[36:37], v[36:37], v[142:143]
	v_pk_mul_f32 v[38:39], v[38:39], v[142:143]
	v_pk_mul_f32 v[40:41], v[40:41], v[142:143]
	v_pk_mul_f32 v[42:43], v[42:43], v[142:143]
	v_pk_mul_f32 v[44:45], v[44:45], v[142:143]
	v_pk_mul_f32 v[46:47], v[46:47], v[142:143]
	v_cvt_pk_bf16_f32 v32, v32, v33
	v_cvt_pk_bf16_f32 v33, v34, v35
	v_cvt_pk_bf16_f32 v36, v36, v37
	v_cvt_pk_bf16_f32 v37, v38, v39
	v_cvt_pk_bf16_f32 v40, v40, v41
	v_cvt_pk_bf16_f32 v41, v42, v43
	v_cvt_pk_bf16_f32 v44, v44, v45
	v_cvt_pk_bf16_f32 v45, v46, v47
	global_store_dwordx2 v74, v[32:33], s[16:17] offset:0
	global_store_dwordx2 v74, v[36:37], s[16:17] offset:32
	global_store_dwordx2 v74, v[40:41], s[16:17] offset:64
	global_store_dwordx2 v74, v[44:45], s[16:17] offset:96
	ds_read_b128 v[32:35], v72 offset:6144
	ds_read_b128 v[36:39], v146 offset:6144
	ds_read_b128 v[40:43], v72 offset:8192
	s_waitcnt lgkmcnt(8)
	v_mfma_f32_16x16x32_bf16 v[78:81], v[48:51], v[8:11], 0
	ds_read_b128 v[44:47], v146 offset:8192
	s_waitcnt lgkmcnt(8)
	v_mfma_f32_16x16x32_bf16 v[78:81], v[52:55], v[12:15], v[78:81]
	ds_read_b128 v[48:51], v72 offset:10240
	s_waitcnt lgkmcnt(8)
	v_mfma_f32_16x16x32_bf16 v[82:85], v[56:59], v[8:11], 0
	ds_read_b128 v[52:55], v146 offset:10240
	s_waitcnt lgkmcnt(8)
	v_mfma_f32_16x16x32_bf16 v[82:85], v[60:63], v[12:15], v[82:85]
	ds_read_b128 v[56:59], v72 offset:12288
	s_waitcnt lgkmcnt(8)
	v_mfma_f32_16x16x32_bf16 v[86:89], v[64:67], v[8:11], 0
	ds_read_b128 v[60:63], v146 offset:12288
	s_waitcnt lgkmcnt(8)
	v_mfma_f32_16x16x32_bf16 v[86:89], v[68:71], v[12:15], v[86:89]
	ds_read_b128 v[64:67], v72 offset:14336
	s_waitcnt lgkmcnt(8)
	v_mfma_f32_16x16x32_bf16 v[90:93], v[32:35], v[8:11], 0
	ds_read_b128 v[68:71], v146 offset:14336
	s_waitcnt lgkmcnt(8)
	v_mfma_f32_16x16x32_bf16 v[90:93], v[36:39], v[12:15], v[90:93]
	ds_read_b128 v[32:35], v72 offset:16384
	s_waitcnt lgkmcnt(8)
	v_mfma_f32_16x16x32_bf16 v[94:97], v[40:43], v[8:11], 0
	ds_read_b128 v[36:39], v146 offset:16384
	s_waitcnt lgkmcnt(8)
	v_mfma_f32_16x16x32_bf16 v[94:97], v[44:47], v[12:15], v[94:97]
	ds_read_b128 v[40:43], v72 offset:18432
	s_waitcnt lgkmcnt(8)
	v_mfma_f32_16x16x32_bf16 v[98:101], v[48:51], v[8:11], 0
	ds_read_b128 v[44:47], v146 offset:18432
	s_waitcnt lgkmcnt(8)
	v_mfma_f32_16x16x32_bf16 v[98:101], v[52:55], v[12:15], v[98:101]
	ds_read_b128 v[48:51], v72 offset:20480
	s_waitcnt lgkmcnt(8)
	v_mfma_f32_16x16x32_bf16 v[102:105], v[56:59], v[8:11], 0
	ds_read_b128 v[52:55], v146 offset:20480
	s_waitcnt lgkmcnt(8)
	v_mfma_f32_16x16x32_bf16 v[102:105], v[60:63], v[12:15], v[102:105]
	ds_read_b128 v[56:59], v72 offset:22528
	s_waitcnt lgkmcnt(8)
	v_mfma_f32_16x16x32_bf16 v[106:109], v[64:67], v[8:11], 0
	ds_read_b128 v[60:63], v146 offset:22528
	s_waitcnt lgkmcnt(8)
	v_mfma_f32_16x16x32_bf16 v[106:109], v[68:71], v[12:15], v[106:109]
	ds_read_b128 v[64:67], v72 offset:24576
	s_waitcnt lgkmcnt(8)
	v_mfma_f32_16x16x32_bf16 v[110:113], v[32:35], v[8:11], 0
	ds_read_b128 v[68:71], v146 offset:24576
	s_waitcnt lgkmcnt(8)
	v_mfma_f32_16x16x32_bf16 v[110:113], v[36:39], v[12:15], v[110:113]
	ds_read_b128 v[32:35], v72 offset:26624
	s_waitcnt lgkmcnt(8)
	v_mfma_f32_16x16x32_bf16 v[114:117], v[40:43], v[8:11], 0
	ds_read_b128 v[36:39], v146 offset:26624
	s_waitcnt lgkmcnt(8)
	v_mfma_f32_16x16x32_bf16 v[114:117], v[44:47], v[12:15], v[114:117]
	ds_read_b128 v[40:43], v72 offset:28672
	s_waitcnt lgkmcnt(8)
	v_mfma_f32_16x16x32_bf16 v[118:121], v[48:51], v[8:11], 0
	ds_read_b128 v[44:47], v146 offset:28672
	s_waitcnt lgkmcnt(8)
	v_mfma_f32_16x16x32_bf16 v[118:121], v[52:55], v[12:15], v[118:121]
	ds_read_b128 v[48:51], v72 offset:30720
	s_waitcnt lgkmcnt(8)
	v_mfma_f32_16x16x32_bf16 v[122:125], v[56:59], v[8:11], 0
	ds_read_b128 v[52:55], v146 offset:30720
	s_waitcnt lgkmcnt(8)
	v_mfma_f32_16x16x32_bf16 v[122:125], v[60:63], v[12:15], v[122:125]
	s_waitcnt lgkmcnt(7)
	v_mfma_f32_16x16x32_bf16 v[126:129], v[64:67], v[8:11], 0
	s_waitcnt lgkmcnt(6)
	v_mfma_f32_16x16x32_bf16 v[126:129], v[68:71], v[12:15], v[126:129]
	s_waitcnt lgkmcnt(5)
	v_mfma_f32_16x16x32_bf16 v[130:133], v[32:35], v[8:11], 0
	s_waitcnt lgkmcnt(4)
	v_mfma_f32_16x16x32_bf16 v[130:133], v[36:39], v[12:15], v[130:133]
	s_waitcnt lgkmcnt(3)
	v_mfma_f32_16x16x32_bf16 v[134:137], v[40:43], v[8:11], 0
	s_waitcnt lgkmcnt(2)
	v_mfma_f32_16x16x32_bf16 v[134:137], v[44:47], v[12:15], v[134:137]
	s_waitcnt lgkmcnt(1)
	v_mfma_f32_16x16x32_bf16 v[138:141], v[48:51], v[8:11], 0
	s_waitcnt lgkmcnt(0)
	v_mfma_f32_16x16x32_bf16 v[138:141], v[52:55], v[12:15], v[138:141]
	ds_read_b64 v[48:49], v73 offset:36864
	ds_read_b64 v[50:51], v73 offset:36896
	ds_read_b64 v[52:53], v73 offset:45312
	ds_read_b64 v[54:55], v73 offset:45344
	ds_read_b64 v[56:57], v73 offset:53760
	ds_read_b64 v[58:59], v73 offset:53792
	ds_read_b64 v[60:61], v73 offset:62208
	ds_read_b64 v[62:63], v73 offset:62240
	ds_read_b64 v[64:65], v73 offset:36928
	ds_read_b64 v[66:67], v73 offset:36960
	ds_read_b64 v[68:69], v73 offset:45376
	ds_read_b64 v[70:71], v73 offset:45408
	v_max3_f32 v36, v78, v79, v80
	v_max3_f32 v36, v36, v81, v82
	v_max3_f32 v36, v36, v83, v84
	v_max3_f32 v36, v36, v85, v86
	v_max3_f32 v36, v36, v87, v88
	v_max3_f32 v36, v36, v89, v90
	v_max3_f32 v36, v36, v91, v92
	v_max3_f32 v36, v36, v93, v94
	v_max3_f32 v36, v36, v95, v96
	v_max3_f32 v36, v36, v97, v98
	v_max3_f32 v36, v36, v99, v100
	v_max3_f32 v36, v36, v101, v102
	v_max3_f32 v36, v36, v103, v104
	v_max3_f32 v36, v36, v105, v106
	v_max3_f32 v36, v36, v107, v108
	v_max3_f32 v36, v36, v109, v110
	v_max3_f32 v36, v36, v111, v112
	v_max3_f32 v36, v36, v113, v114
	v_max3_f32 v36, v36, v115, v116
	v_max3_f32 v36, v36, v117, v118
	v_max3_f32 v36, v36, v119, v120
	v_max3_f32 v36, v36, v121, v122
	v_max3_f32 v36, v36, v123, v124
	v_max3_f32 v36, v36, v125, v126
	v_max3_f32 v36, v36, v127, v128
	v_max3_f32 v36, v36, v129, v130
	v_max3_f32 v36, v36, v131, v132
	v_max3_f32 v36, v36, v133, v134
	v_max3_f32 v36, v36, v135, v136
	v_max3_f32 v36, v36, v137, v138
	v_max3_f32 v36, v36, v139, v140
	v_max_f32_e32 v36, v36, v141
	v_mov_b32_e32 v37, v36
	s_nop 1
	v_permlane16_swap_b32_e32 v36, v37
	v_max_f32_e32 v36, v36, v37
	v_mov_b32_e32 v37, v36
	s_nop 1
	v_permlane32_swap_b32_e32 v36, v37
	v_max_f32_e32 v36, v36, v37
	v_mul_f32_e64 v38, v36, -v144
	v_mov_b32_e32 v40, 0
	v_mov_b32_e32 v41, 0
	v_mov_b32_e32 v39, v38
	v_pk_fma_f32 v[78:79], v[78:79], v[144:145], v[38:39]
	v_pk_fma_f32 v[80:81], v[80:81], v[144:145], v[38:39]
	v_exp_f32_e32 v78, v78
	v_exp_f32_e32 v79, v79
	v_exp_f32_e32 v80, v80
	v_exp_f32_e32 v81, v81
	v_pk_fma_f32 v[82:83], v[82:83], v[144:145], v[38:39]
	v_pk_fma_f32 v[84:85], v[84:85], v[144:145], v[38:39]
	v_exp_f32_e32 v82, v82
	v_exp_f32_e32 v83, v83
	v_exp_f32_e32 v84, v84
	v_exp_f32_e32 v85, v85
	v_pk_add_f32 v[40:41], v[40:41], v[78:79]
	v_pk_add_f32 v[40:41], v[40:41], v[80:81]
	v_pk_fma_f32 v[86:87], v[86:87], v[144:145], v[38:39]
	v_pk_fma_f32 v[88:89], v[88:89], v[144:145], v[38:39]
	v_exp_f32_e32 v86, v86
	v_exp_f32_e32 v87, v87
	v_exp_f32_e32 v88, v88
	v_exp_f32_e32 v89, v89
	v_pk_add_f32 v[40:41], v[40:41], v[82:83]
	v_pk_add_f32 v[40:41], v[40:41], v[84:85]
	v_pk_fma_f32 v[90:91], v[90:91], v[144:145], v[38:39]
	v_pk_fma_f32 v[92:93], v[92:93], v[144:145], v[38:39]
	v_exp_f32_e32 v90, v90
	v_exp_f32_e32 v91, v91
	v_exp_f32_e32 v92, v92
	v_exp_f32_e32 v93, v93
	v_pk_add_f32 v[40:41], v[40:41], v[86:87]
	v_pk_add_f32 v[40:41], v[40:41], v[88:89]
	v_pk_fma_f32 v[94:95], v[94:95], v[144:145], v[38:39]
	v_pk_fma_f32 v[96:97], v[96:97], v[144:145], v[38:39]
	v_exp_f32_e32 v94, v94
	v_exp_f32_e32 v95, v95
	v_exp_f32_e32 v96, v96
	v_exp_f32_e32 v97, v97
	v_pk_add_f32 v[40:41], v[40:41], v[90:91]
	v_pk_add_f32 v[40:41], v[40:41], v[92:93]
	v_pk_fma_f32 v[98:99], v[98:99], v[144:145], v[38:39]
	v_pk_fma_f32 v[100:101], v[100:101], v[144:145], v[38:39]
	v_exp_f32_e32 v98, v98
	v_exp_f32_e32 v99, v99
	v_exp_f32_e32 v100, v100
	v_exp_f32_e32 v101, v101
	v_pk_add_f32 v[40:41], v[40:41], v[94:95]
	v_pk_add_f32 v[40:41], v[40:41], v[96:97]
	v_pk_fma_f32 v[102:103], v[102:103], v[144:145], v[38:39]
	v_pk_fma_f32 v[104:105], v[104:105], v[144:145], v[38:39]
	v_exp_f32_e32 v102, v102
	v_exp_f32_e32 v103, v103
	v_exp_f32_e32 v104, v104
	v_exp_f32_e32 v105, v105
	v_pk_add_f32 v[40:41], v[40:41], v[98:99]
	v_pk_add_f32 v[40:41], v[40:41], v[100:101]
	v_pk_fma_f32 v[106:107], v[106:107], v[144:145], v[38:39]
	v_pk_fma_f32 v[108:109], v[108:109], v[144:145], v[38:39]
	v_exp_f32_e32 v106, v106
	v_exp_f32_e32 v107, v107
	v_exp_f32_e32 v108, v108
	v_exp_f32_e32 v109, v109
	v_pk_add_f32 v[40:41], v[40:41], v[102:103]
	v_pk_add_f32 v[40:41], v[40:41], v[104:105]
	v_pk_fma_f32 v[110:111], v[110:111], v[144:145], v[38:39]
	v_pk_fma_f32 v[112:113], v[112:113], v[144:145], v[38:39]
	v_exp_f32_e32 v110, v110
	v_exp_f32_e32 v111, v111
	v_exp_f32_e32 v112, v112
	v_exp_f32_e32 v113, v113
	v_pk_add_f32 v[40:41], v[40:41], v[106:107]
	v_pk_add_f32 v[40:41], v[40:41], v[108:109]
	v_pk_fma_f32 v[114:115], v[114:115], v[144:145], v[38:39]
	v_pk_fma_f32 v[116:117], v[116:117], v[144:145], v[38:39]
	v_exp_f32_e32 v114, v114
	v_exp_f32_e32 v115, v115
	v_exp_f32_e32 v116, v116
	v_exp_f32_e32 v117, v117
	v_pk_add_f32 v[40:41], v[40:41], v[110:111]
	v_pk_add_f32 v[40:41], v[40:41], v[112:113]
	v_pk_fma_f32 v[118:119], v[118:119], v[144:145], v[38:39]
	v_pk_fma_f32 v[120:121], v[120:121], v[144:145], v[38:39]
	v_exp_f32_e32 v118, v118
	v_exp_f32_e32 v119, v119
	v_exp_f32_e32 v120, v120
	v_exp_f32_e32 v121, v121
	v_pk_add_f32 v[40:41], v[40:41], v[114:115]
	v_pk_add_f32 v[40:41], v[40:41], v[116:117]
	v_pk_fma_f32 v[122:123], v[122:123], v[144:145], v[38:39]
	v_pk_fma_f32 v[124:125], v[124:125], v[144:145], v[38:39]
	v_exp_f32_e32 v122, v122
	v_exp_f32_e32 v123, v123
	v_exp_f32_e32 v124, v124
	v_exp_f32_e32 v125, v125
	v_pk_add_f32 v[40:41], v[40:41], v[118:119]
	v_pk_add_f32 v[40:41], v[40:41], v[120:121]
	v_pk_fma_f32 v[126:127], v[126:127], v[144:145], v[38:39]
	v_pk_fma_f32 v[128:129], v[128:129], v[144:145], v[38:39]
	v_exp_f32_e32 v126, v126
	v_exp_f32_e32 v127, v127
	v_exp_f32_e32 v128, v128
	v_exp_f32_e32 v129, v129
	v_pk_add_f32 v[40:41], v[40:41], v[122:123]
	v_pk_add_f32 v[40:41], v[40:41], v[124:125]
	v_pk_fma_f32 v[130:131], v[130:131], v[144:145], v[38:39]
	v_pk_fma_f32 v[132:133], v[132:133], v[144:145], v[38:39]
	v_exp_f32_e32 v130, v130
	v_exp_f32_e32 v131, v131
	v_exp_f32_e32 v132, v132
	v_exp_f32_e32 v133, v133
	v_pk_add_f32 v[40:41], v[40:41], v[126:127]
	v_pk_add_f32 v[40:41], v[40:41], v[128:129]
	v_pk_fma_f32 v[134:135], v[134:135], v[144:145], v[38:39]
	v_pk_fma_f32 v[136:137], v[136:137], v[144:145], v[38:39]
	v_exp_f32_e32 v134, v134
	v_exp_f32_e32 v135, v135
	v_exp_f32_e32 v136, v136
	v_exp_f32_e32 v137, v137
	v_pk_add_f32 v[40:41], v[40:41], v[130:131]
	v_pk_add_f32 v[40:41], v[40:41], v[132:133]
	v_pk_fma_f32 v[138:139], v[138:139], v[144:145], v[38:39]
	v_pk_fma_f32 v[140:141], v[140:141], v[144:145], v[38:39]
	v_exp_f32_e32 v138, v138
	v_exp_f32_e32 v139, v139
	v_exp_f32_e32 v140, v140
	v_exp_f32_e32 v141, v141
	v_pk_add_f32 v[40:41], v[40:41], v[134:135]
	v_pk_add_f32 v[40:41], v[40:41], v[136:137]
	s_nop 0
	v_pk_add_f32 v[40:41], v[40:41], v[138:139]
	v_pk_add_f32 v[40:41], v[40:41], v[140:141]
	v_add_f32_e32 v36, v40, v41
	v_mov_b32_e32 v37, v36
	s_nop 1
	v_permlane16_swap_b32_e32 v36, v37
	v_add_f32_e32 v36, v36, v37
	v_mov_b32_e32 v37, v36
	s_nop 1
	v_permlane32_swap_b32_e32 v36, v37
	v_add_f32_e32 v36, v36, v37
	v_rcp_f32_e32 v142, v36
	v_cvt_pk_bf16_f32 v78, v78, v79
	v_cvt_pk_bf16_f32 v79, v80, v81
	v_cvt_pk_bf16_f32 v80, v82, v83
	v_cvt_pk_bf16_f32 v81, v84, v85
	v_cvt_pk_bf16_f32 v86, v86, v87
	v_cvt_pk_bf16_f32 v87, v88, v89
	v_cvt_pk_bf16_f32 v88, v90, v91
	v_cvt_pk_bf16_f32 v89, v92, v93
	v_cvt_pk_bf16_f32 v94, v94, v95
	v_cvt_pk_bf16_f32 v95, v96, v97
	v_cvt_pk_bf16_f32 v96, v98, v99
	v_cvt_pk_bf16_f32 v97, v100, v101
	v_cvt_pk_bf16_f32 v102, v102, v103
	v_cvt_pk_bf16_f32 v103, v104, v105
	v_cvt_pk_bf16_f32 v104, v106, v107
	v_cvt_pk_bf16_f32 v105, v108, v109
	v_cvt_pk_bf16_f32 v110, v110, v111
	v_cvt_pk_bf16_f32 v111, v112, v113
	v_cvt_pk_bf16_f32 v112, v114, v115
	v_cvt_pk_bf16_f32 v113, v116, v117
	v_cvt_pk_bf16_f32 v118, v118, v119
	v_cvt_pk_bf16_f32 v119, v120, v121
	v_cvt_pk_bf16_f32 v120, v122, v123
	v_cvt_pk_bf16_f32 v121, v124, v125
	v_cvt_pk_bf16_f32 v126, v126, v127
	v_cvt_pk_bf16_f32 v127, v128, v129
	v_cvt_pk_bf16_f32 v128, v130, v131
	v_cvt_pk_bf16_f32 v129, v132, v133
	v_cvt_pk_bf16_f32 v134, v134, v135
	v_cvt_pk_bf16_f32 v135, v136, v137
	v_cvt_pk_bf16_f32 v136, v138, v139
	v_cvt_pk_bf16_f32 v137, v140, v141
	v_fma_f32 v143, -v36, v142, 1.0
	v_fma_f32 v142, v143, v142, v142
	v_mov_b32_e32 v143, v142
	ds_read_b64 v[82:83], v73 offset:53824
	ds_read_b64 v[84:85], v73 offset:53856
	s_waitcnt lgkmcnt(12)
	v_mfma_f32_16x16x32_bf16 v[32:35], v[48:51], v[78:81], 0
	ds_read_b64 v[90:91], v73 offset:62272
	ds_read_b64 v[92:93], v73 offset:62304
	s_waitcnt lgkmcnt(12)
	v_mfma_f32_16x16x32_bf16 v[36:39], v[52:55], v[78:81], 0
	ds_read_b64 v[48:49], v73 offset:36992
	ds_read_b64 v[50:51], v73 offset:37024
	s_waitcnt lgkmcnt(12)
	v_mfma_f32_16x16x32_bf16 v[40:43], v[56:59], v[78:81], 0
	ds_read_b64 v[52:53], v73 offset:45440
	ds_read_b64 v[54:55], v73 offset:45472
	s_waitcnt lgkmcnt(12)
	v_mfma_f32_16x16x32_bf16 v[44:47], v[60:63], v[78:81], 0
	ds_read_b64 v[56:57], v73 offset:53888
	ds_read_b64 v[58:59], v73 offset:53920
	s_waitcnt lgkmcnt(12)
	v_mfma_f32_16x16x32_bf16 v[32:35], v[64:67], v[86:89], v[32:35]
	ds_read_b64 v[60:61], v73 offset:62336
	ds_read_b64 v[62:63], v73 offset:62368
	s_waitcnt lgkmcnt(12)
	v_mfma_f32_16x16x32_bf16 v[36:39], v[68:71], v[86:89], v[36:39]
	ds_read_b64 v[64:65], v73 offset:37056
	ds_read_b64 v[66:67], v73 offset:37088
	s_waitcnt lgkmcnt(12)
	v_mfma_f32_16x16x32_bf16 v[40:43], v[82:85], v[86:89], v[40:43]
	ds_read_b64 v[68:69], v73 offset:45504
	ds_read_b64 v[70:71], v73 offset:45536
	s_waitcnt lgkmcnt(12)
	v_mfma_f32_16x16x32_bf16 v[44:47], v[90:93], v[86:89], v[44:47]
	ds_read_b64 v[82:83], v73 offset:53952
	ds_read_b64 v[84:85], v73 offset:53984
	s_waitcnt lgkmcnt(12)
	v_mfma_f32_16x16x32_bf16 v[32:35], v[48:51], v[94:97], v[32:35]
	ds_read_b64 v[90:91], v73 offset:62400
	ds_read_b64 v[92:93], v73 offset:62432
	s_waitcnt lgkmcnt(12)
	v_mfma_f32_16x16x32_bf16 v[36:39], v[52:55], v[94:97], v[36:39]
	ds_read_b64 v[48:49], v73 offset:37120
	ds_read_b64 v[50:51], v73 offset:37152
	s_waitcnt lgkmcnt(12)
	v_mfma_f32_16x16x32_bf16 v[40:43], v[56:59], v[94:97], v[40:43]
	ds_read_b64 v[52:53], v73 offset:45568
	ds_read_b64 v[54:55], v73 offset:45600
	s_waitcnt lgkmcnt(12)
	v_mfma_f32_16x16x32_bf16 v[44:47], v[60:63], v[94:97], v[44:47]
	ds_read_b64 v[56:57], v73 offset:54016
	ds_read_b64 v[58:59], v73 offset:54048
	s_waitcnt lgkmcnt(12)
	v_mfma_f32_16x16x32_bf16 v[32:35], v[64:67], v[102:105], v[32:35]
	ds_read_b64 v[60:61], v73 offset:62464
	ds_read_b64 v[62:63], v73 offset:62496
	s_waitcnt lgkmcnt(12)
	v_mfma_f32_16x16x32_bf16 v[36:39], v[68:71], v[102:105], v[36:39]
	ds_read_b64 v[64:65], v73 offset:37184
	ds_read_b64 v[66:67], v73 offset:37216
	s_waitcnt lgkmcnt(12)
	v_mfma_f32_16x16x32_bf16 v[40:43], v[82:85], v[102:105], v[40:43]
	ds_read_b64 v[68:69], v73 offset:45632
	ds_read_b64 v[70:71], v73 offset:45664
	s_waitcnt lgkmcnt(12)
	v_mfma_f32_16x16x32_bf16 v[44:47], v[90:93], v[102:105], v[44:47]
	ds_read_b64 v[82:83], v73 offset:54080
	ds_read_b64 v[84:85], v73 offset:54112
	s_waitcnt lgkmcnt(12)
	v_mfma_f32_16x16x32_bf16 v[32:35], v[48:51], v[110:113], v[32:35]
	ds_read_b64 v[90:91], v73 offset:62528
	ds_read_b64 v[92:93], v73 offset:62560
	s_waitcnt lgkmcnt(12)
	v_mfma_f32_16x16x32_bf16 v[36:39], v[52:55], v[110:113], v[36:39]
	ds_read_b64 v[48:49], v73 offset:37248
	ds_read_b64 v[50:51], v73 offset:37280
	s_waitcnt lgkmcnt(12)
	v_mfma_f32_16x16x32_bf16 v[40:43], v[56:59], v[110:113], v[40:43]
	ds_read_b64 v[52:53], v73 offset:45696
	ds_read_b64 v[54:55], v73 offset:45728
	s_waitcnt lgkmcnt(12)
	v_mfma_f32_16x16x32_bf16 v[44:47], v[60:63], v[110:113], v[44:47]
	ds_read_b64 v[56:57], v73 offset:54144
	ds_read_b64 v[58:59], v73 offset:54176
	s_waitcnt lgkmcnt(12)
	v_mfma_f32_16x16x32_bf16 v[32:35], v[64:67], v[118:121], v[32:35]
	ds_read_b64 v[60:61], v73 offset:62592
	ds_read_b64 v[62:63], v73 offset:62624
	s_waitcnt lgkmcnt(12)
	v_mfma_f32_16x16x32_bf16 v[36:39], v[68:71], v[118:121], v[36:39]
	ds_read_b64 v[64:65], v73 offset:37312
	ds_read_b64 v[66:67], v73 offset:37344
	s_waitcnt lgkmcnt(12)
	v_mfma_f32_16x16x32_bf16 v[40:43], v[82:85], v[118:121], v[40:43]
	ds_read_b64 v[68:69], v73 offset:45760
	ds_read_b64 v[70:71], v73 offset:45792
	s_waitcnt lgkmcnt(12)
	v_mfma_f32_16x16x32_bf16 v[44:47], v[90:93], v[118:121], v[44:47]
	ds_read_b64 v[82:83], v73 offset:54208
	ds_read_b64 v[84:85], v73 offset:54240
	s_waitcnt lgkmcnt(12)
	v_mfma_f32_16x16x32_bf16 v[32:35], v[48:51], v[126:129], v[32:35]
	ds_read_b64 v[90:91], v73 offset:62656
	ds_read_b64 v[92:93], v73 offset:62688
	s_waitcnt lgkmcnt(12)
	v_mfma_f32_16x16x32_bf16 v[36:39], v[52:55], v[126:129], v[36:39]
	s_waitcnt lgkmcnt(10)
	v_mfma_f32_16x16x32_bf16 v[40:43], v[56:59], v[126:129], v[40:43]
	s_waitcnt lgkmcnt(8)
	v_mfma_f32_16x16x32_bf16 v[44:47], v[60:63], v[126:129], v[44:47]
	s_waitcnt lgkmcnt(6)
	v_mfma_f32_16x16x32_bf16 v[32:35], v[64:67], v[134:137], v[32:35]
	s_waitcnt lgkmcnt(4)
	v_mfma_f32_16x16x32_bf16 v[36:39], v[68:71], v[134:137], v[36:39]
	s_waitcnt lgkmcnt(2)
	v_mfma_f32_16x16x32_bf16 v[40:43], v[82:85], v[134:137], v[40:43]
	s_waitcnt lgkmcnt(0)
	v_mfma_f32_16x16x32_bf16 v[44:47], v[90:93], v[134:137], v[44:47]
	ds_read_b128 v[48:51], v72 offset:0
	ds_read_b128 v[52:55], v146 offset:0
	ds_read_b128 v[56:59], v72 offset:2048
	ds_read_b128 v[60:63], v146 offset:2048
	ds_read_b128 v[64:67], v72 offset:4096
	ds_read_b128 v[68:71], v146 offset:4096
	s_add_u32 s16, s12, 0x8000
	s_addc_u32 s17, s13, 0
	s_nop 7
	v_pk_mul_f32 v[32:33], v[32:33], v[142:143]
	v_pk_mul_f32 v[34:35], v[34:35], v[142:143]
	v_pk_mul_f32 v[36:37], v[36:37], v[142:143]
	v_pk_mul_f32 v[38:39], v[38:39], v[142:143]
	v_pk_mul_f32 v[40:41], v[40:41], v[142:143]
	v_pk_mul_f32 v[42:43], v[42:43], v[142:143]
	v_pk_mul_f32 v[44:45], v[44:45], v[142:143]
	v_pk_mul_f32 v[46:47], v[46:47], v[142:143]
	v_cvt_pk_bf16_f32 v32, v32, v33
	v_cvt_pk_bf16_f32 v33, v34, v35
	v_cvt_pk_bf16_f32 v36, v36, v37
	v_cvt_pk_bf16_f32 v37, v38, v39
	v_cvt_pk_bf16_f32 v40, v40, v41
	v_cvt_pk_bf16_f32 v41, v42, v43
	v_cvt_pk_bf16_f32 v44, v44, v45
	v_cvt_pk_bf16_f32 v45, v46, v47
	global_store_dwordx2 v74, v[32:33], s[16:17] offset:0
	global_store_dwordx2 v74, v[36:37], s[16:17] offset:32
	global_store_dwordx2 v74, v[40:41], s[16:17] offset:64
	global_store_dwordx2 v74, v[44:45], s[16:17] offset:96
	ds_read_b128 v[32:35], v72 offset:6144
	ds_read_b128 v[36:39], v146 offset:6144
	ds_read_b128 v[40:43], v72 offset:8192
	s_waitcnt lgkmcnt(8)
	v_mfma_f32_16x16x32_bf16 v[78:81], v[48:51], v[16:19], 0
	ds_read_b128 v[44:47], v146 offset:8192
	s_waitcnt lgkmcnt(8)
	v_mfma_f32_16x16x32_bf16 v[78:81], v[52:55], v[20:23], v[78:81]
	ds_read_b128 v[48:51], v72 offset:10240
	s_waitcnt lgkmcnt(8)
	v_mfma_f32_16x16x32_bf16 v[82:85], v[56:59], v[16:19], 0
	ds_read_b128 v[52:55], v146 offset:10240
	s_waitcnt lgkmcnt(8)
	v_mfma_f32_16x16x32_bf16 v[82:85], v[60:63], v[20:23], v[82:85]
	ds_read_b128 v[56:59], v72 offset:12288
	s_waitcnt lgkmcnt(8)
	v_mfma_f32_16x16x32_bf16 v[86:89], v[64:67], v[16:19], 0
	ds_read_b128 v[60:63], v146 offset:12288
	s_waitcnt lgkmcnt(8)
	v_mfma_f32_16x16x32_bf16 v[86:89], v[68:71], v[20:23], v[86:89]
	ds_read_b128 v[64:67], v72 offset:14336
	s_waitcnt lgkmcnt(8)
	v_mfma_f32_16x16x32_bf16 v[90:93], v[32:35], v[16:19], 0
	ds_read_b128 v[68:71], v146 offset:14336
	s_waitcnt lgkmcnt(8)
	v_mfma_f32_16x16x32_bf16 v[90:93], v[36:39], v[20:23], v[90:93]
	ds_read_b128 v[32:35], v72 offset:16384
	s_waitcnt lgkmcnt(8)
	v_mfma_f32_16x16x32_bf16 v[94:97], v[40:43], v[16:19], 0
	ds_read_b128 v[36:39], v146 offset:16384
	s_waitcnt lgkmcnt(8)
	v_mfma_f32_16x16x32_bf16 v[94:97], v[44:47], v[20:23], v[94:97]
	ds_read_b128 v[40:43], v72 offset:18432
	s_waitcnt lgkmcnt(8)
	v_mfma_f32_16x16x32_bf16 v[98:101], v[48:51], v[16:19], 0
	ds_read_b128 v[44:47], v146 offset:18432
	s_waitcnt lgkmcnt(8)
	v_mfma_f32_16x16x32_bf16 v[98:101], v[52:55], v[20:23], v[98:101]
	ds_read_b128 v[48:51], v72 offset:20480
	s_waitcnt lgkmcnt(8)
	v_mfma_f32_16x16x32_bf16 v[102:105], v[56:59], v[16:19], 0
	ds_read_b128 v[52:55], v146 offset:20480
	s_waitcnt lgkmcnt(8)
	v_mfma_f32_16x16x32_bf16 v[102:105], v[60:63], v[20:23], v[102:105]
	ds_read_b128 v[56:59], v72 offset:22528
	s_waitcnt lgkmcnt(8)
	v_mfma_f32_16x16x32_bf16 v[106:109], v[64:67], v[16:19], 0
	ds_read_b128 v[60:63], v146 offset:22528
	s_waitcnt lgkmcnt(8)
	v_mfma_f32_16x16x32_bf16 v[106:109], v[68:71], v[20:23], v[106:109]
	ds_read_b128 v[64:67], v72 offset:24576
	s_waitcnt lgkmcnt(8)
	v_mfma_f32_16x16x32_bf16 v[110:113], v[32:35], v[16:19], 0
	ds_read_b128 v[68:71], v146 offset:24576
	s_waitcnt lgkmcnt(8)
	v_mfma_f32_16x16x32_bf16 v[110:113], v[36:39], v[20:23], v[110:113]
	ds_read_b128 v[32:35], v72 offset:26624
	s_waitcnt lgkmcnt(8)
	v_mfma_f32_16x16x32_bf16 v[114:117], v[40:43], v[16:19], 0
	ds_read_b128 v[36:39], v146 offset:26624
	s_waitcnt lgkmcnt(8)
	v_mfma_f32_16x16x32_bf16 v[114:117], v[44:47], v[20:23], v[114:117]
	ds_read_b128 v[40:43], v72 offset:28672
	s_waitcnt lgkmcnt(8)
	v_mfma_f32_16x16x32_bf16 v[118:121], v[48:51], v[16:19], 0
	ds_read_b128 v[44:47], v146 offset:28672
	s_waitcnt lgkmcnt(8)
	v_mfma_f32_16x16x32_bf16 v[118:121], v[52:55], v[20:23], v[118:121]
	ds_read_b128 v[48:51], v72 offset:30720
	s_waitcnt lgkmcnt(8)
	v_mfma_f32_16x16x32_bf16 v[122:125], v[56:59], v[16:19], 0
	ds_read_b128 v[52:55], v146 offset:30720
	s_waitcnt lgkmcnt(8)
	v_mfma_f32_16x16x32_bf16 v[122:125], v[60:63], v[20:23], v[122:125]
	s_waitcnt lgkmcnt(7)
	v_mfma_f32_16x16x32_bf16 v[126:129], v[64:67], v[16:19], 0
	s_waitcnt lgkmcnt(6)
	v_mfma_f32_16x16x32_bf16 v[126:129], v[68:71], v[20:23], v[126:129]
	s_waitcnt lgkmcnt(5)
	v_mfma_f32_16x16x32_bf16 v[130:133], v[32:35], v[16:19], 0
	s_waitcnt lgkmcnt(4)
	v_mfma_f32_16x16x32_bf16 v[130:133], v[36:39], v[20:23], v[130:133]
	s_waitcnt lgkmcnt(3)
	v_mfma_f32_16x16x32_bf16 v[134:137], v[40:43], v[16:19], 0
	s_waitcnt lgkmcnt(2)
	v_mfma_f32_16x16x32_bf16 v[134:137], v[44:47], v[20:23], v[134:137]
	s_waitcnt lgkmcnt(1)
	v_mfma_f32_16x16x32_bf16 v[138:141], v[48:51], v[16:19], 0
	s_waitcnt lgkmcnt(0)
	v_mfma_f32_16x16x32_bf16 v[138:141], v[52:55], v[20:23], v[138:141]
	ds_read_b64 v[48:49], v73 offset:36864
	ds_read_b64 v[50:51], v73 offset:36896
	ds_read_b64 v[52:53], v73 offset:45312
	ds_read_b64 v[54:55], v73 offset:45344
	ds_read_b64 v[56:57], v73 offset:53760
	ds_read_b64 v[58:59], v73 offset:53792
	ds_read_b64 v[60:61], v73 offset:62208
	ds_read_b64 v[62:63], v73 offset:62240
	ds_read_b64 v[64:65], v73 offset:36928
	ds_read_b64 v[66:67], v73 offset:36960
	ds_read_b64 v[68:69], v73 offset:45376
	ds_read_b64 v[70:71], v73 offset:45408
	v_max3_f32 v36, v78, v79, v80
	v_max3_f32 v36, v36, v81, v82
	v_max3_f32 v36, v36, v83, v84
	v_max3_f32 v36, v36, v85, v86
	v_max3_f32 v36, v36, v87, v88
	v_max3_f32 v36, v36, v89, v90
	v_max3_f32 v36, v36, v91, v92
	v_max3_f32 v36, v36, v93, v94
	v_max3_f32 v36, v36, v95, v96
	v_max3_f32 v36, v36, v97, v98
	v_max3_f32 v36, v36, v99, v100
	v_max3_f32 v36, v36, v101, v102
	v_max3_f32 v36, v36, v103, v104
	v_max3_f32 v36, v36, v105, v106
	v_max3_f32 v36, v36, v107, v108
	v_max3_f32 v36, v36, v109, v110
	v_max3_f32 v36, v36, v111, v112
	v_max3_f32 v36, v36, v113, v114
	v_max3_f32 v36, v36, v115, v116
	v_max3_f32 v36, v36, v117, v118
	v_max3_f32 v36, v36, v119, v120
	v_max3_f32 v36, v36, v121, v122
	v_max3_f32 v36, v36, v123, v124
	v_max3_f32 v36, v36, v125, v126
	v_max3_f32 v36, v36, v127, v128
	v_max3_f32 v36, v36, v129, v130
	v_max3_f32 v36, v36, v131, v132
	v_max3_f32 v36, v36, v133, v134
	v_max3_f32 v36, v36, v135, v136
	v_max3_f32 v36, v36, v137, v138
	v_max3_f32 v36, v36, v139, v140
	v_max_f32_e32 v36, v36, v141
	v_mov_b32_e32 v37, v36
	s_nop 1
	v_permlane16_swap_b32_e32 v36, v37
	v_max_f32_e32 v36, v36, v37
	v_mov_b32_e32 v37, v36
	s_nop 1
	v_permlane32_swap_b32_e32 v36, v37
	v_max_f32_e32 v36, v36, v37
	v_mul_f32_e64 v38, v36, -v144
	v_mov_b32_e32 v40, 0
	v_mov_b32_e32 v41, 0
	v_mov_b32_e32 v39, v38
	v_pk_fma_f32 v[78:79], v[78:79], v[144:145], v[38:39]
	v_pk_fma_f32 v[80:81], v[80:81], v[144:145], v[38:39]
	v_exp_f32_e32 v78, v78
	v_exp_f32_e32 v79, v79
	v_exp_f32_e32 v80, v80
	v_exp_f32_e32 v81, v81
	v_pk_fma_f32 v[82:83], v[82:83], v[144:145], v[38:39]
	v_pk_fma_f32 v[84:85], v[84:85], v[144:145], v[38:39]
	v_exp_f32_e32 v82, v82
	v_exp_f32_e32 v83, v83
	v_exp_f32_e32 v84, v84
	v_exp_f32_e32 v85, v85
	v_pk_add_f32 v[40:41], v[40:41], v[78:79]
	v_pk_add_f32 v[40:41], v[40:41], v[80:81]
	v_pk_fma_f32 v[86:87], v[86:87], v[144:145], v[38:39]
	v_pk_fma_f32 v[88:89], v[88:89], v[144:145], v[38:39]
	v_exp_f32_e32 v86, v86
	v_exp_f32_e32 v87, v87
	v_exp_f32_e32 v88, v88
	v_exp_f32_e32 v89, v89
	v_pk_add_f32 v[40:41], v[40:41], v[82:83]
	v_pk_add_f32 v[40:41], v[40:41], v[84:85]
	v_pk_fma_f32 v[90:91], v[90:91], v[144:145], v[38:39]
	v_pk_fma_f32 v[92:93], v[92:93], v[144:145], v[38:39]
	v_exp_f32_e32 v90, v90
	v_exp_f32_e32 v91, v91
	v_exp_f32_e32 v92, v92
	v_exp_f32_e32 v93, v93
	v_pk_add_f32 v[40:41], v[40:41], v[86:87]
	v_pk_add_f32 v[40:41], v[40:41], v[88:89]
	v_pk_fma_f32 v[94:95], v[94:95], v[144:145], v[38:39]
	v_pk_fma_f32 v[96:97], v[96:97], v[144:145], v[38:39]
	v_exp_f32_e32 v94, v94
	v_exp_f32_e32 v95, v95
	v_exp_f32_e32 v96, v96
	v_exp_f32_e32 v97, v97
	v_pk_add_f32 v[40:41], v[40:41], v[90:91]
	v_pk_add_f32 v[40:41], v[40:41], v[92:93]
	v_pk_fma_f32 v[98:99], v[98:99], v[144:145], v[38:39]
	v_pk_fma_f32 v[100:101], v[100:101], v[144:145], v[38:39]
	v_exp_f32_e32 v98, v98
	v_exp_f32_e32 v99, v99
	v_exp_f32_e32 v100, v100
	v_exp_f32_e32 v101, v101
	v_pk_add_f32 v[40:41], v[40:41], v[94:95]
	v_pk_add_f32 v[40:41], v[40:41], v[96:97]
	v_pk_fma_f32 v[102:103], v[102:103], v[144:145], v[38:39]
	v_pk_fma_f32 v[104:105], v[104:105], v[144:145], v[38:39]
	v_exp_f32_e32 v102, v102
	v_exp_f32_e32 v103, v103
	v_exp_f32_e32 v104, v104
	v_exp_f32_e32 v105, v105
	v_pk_add_f32 v[40:41], v[40:41], v[98:99]
	v_pk_add_f32 v[40:41], v[40:41], v[100:101]
	v_pk_fma_f32 v[106:107], v[106:107], v[144:145], v[38:39]
	v_pk_fma_f32 v[108:109], v[108:109], v[144:145], v[38:39]
	v_exp_f32_e32 v106, v106
	v_exp_f32_e32 v107, v107
	v_exp_f32_e32 v108, v108
	v_exp_f32_e32 v109, v109
	v_pk_add_f32 v[40:41], v[40:41], v[102:103]
	v_pk_add_f32 v[40:41], v[40:41], v[104:105]
	v_pk_fma_f32 v[110:111], v[110:111], v[144:145], v[38:39]
	v_pk_fma_f32 v[112:113], v[112:113], v[144:145], v[38:39]
	v_exp_f32_e32 v110, v110
	v_exp_f32_e32 v111, v111
	v_exp_f32_e32 v112, v112
	v_exp_f32_e32 v113, v113
	v_pk_add_f32 v[40:41], v[40:41], v[106:107]
	v_pk_add_f32 v[40:41], v[40:41], v[108:109]
	v_pk_fma_f32 v[114:115], v[114:115], v[144:145], v[38:39]
	v_pk_fma_f32 v[116:117], v[116:117], v[144:145], v[38:39]
	v_exp_f32_e32 v114, v114
	v_exp_f32_e32 v115, v115
	v_exp_f32_e32 v116, v116
	v_exp_f32_e32 v117, v117
	v_pk_add_f32 v[40:41], v[40:41], v[110:111]
	v_pk_add_f32 v[40:41], v[40:41], v[112:113]
	v_pk_fma_f32 v[118:119], v[118:119], v[144:145], v[38:39]
	v_pk_fma_f32 v[120:121], v[120:121], v[144:145], v[38:39]
	v_exp_f32_e32 v118, v118
	v_exp_f32_e32 v119, v119
	v_exp_f32_e32 v120, v120
	v_exp_f32_e32 v121, v121
	v_pk_add_f32 v[40:41], v[40:41], v[114:115]
	v_pk_add_f32 v[40:41], v[40:41], v[116:117]
	v_pk_fma_f32 v[122:123], v[122:123], v[144:145], v[38:39]
	v_pk_fma_f32 v[124:125], v[124:125], v[144:145], v[38:39]
	v_exp_f32_e32 v122, v122
	v_exp_f32_e32 v123, v123
	v_exp_f32_e32 v124, v124
	v_exp_f32_e32 v125, v125
	v_pk_add_f32 v[40:41], v[40:41], v[118:119]
	v_pk_add_f32 v[40:41], v[40:41], v[120:121]
	v_pk_fma_f32 v[126:127], v[126:127], v[144:145], v[38:39]
	v_pk_fma_f32 v[128:129], v[128:129], v[144:145], v[38:39]
	v_exp_f32_e32 v126, v126
	v_exp_f32_e32 v127, v127
	v_exp_f32_e32 v128, v128
	v_exp_f32_e32 v129, v129
	v_pk_add_f32 v[40:41], v[40:41], v[122:123]
	v_pk_add_f32 v[40:41], v[40:41], v[124:125]
	v_pk_fma_f32 v[130:131], v[130:131], v[144:145], v[38:39]
	v_pk_fma_f32 v[132:133], v[132:133], v[144:145], v[38:39]
	v_exp_f32_e32 v130, v130
	v_exp_f32_e32 v131, v131
	v_exp_f32_e32 v132, v132
	v_exp_f32_e32 v133, v133
	v_pk_add_f32 v[40:41], v[40:41], v[126:127]
	v_pk_add_f32 v[40:41], v[40:41], v[128:129]
	v_pk_fma_f32 v[134:135], v[134:135], v[144:145], v[38:39]
	v_pk_fma_f32 v[136:137], v[136:137], v[144:145], v[38:39]
	v_exp_f32_e32 v134, v134
	v_exp_f32_e32 v135, v135
	v_exp_f32_e32 v136, v136
	v_exp_f32_e32 v137, v137
	v_pk_add_f32 v[40:41], v[40:41], v[130:131]
	v_pk_add_f32 v[40:41], v[40:41], v[132:133]
	v_pk_fma_f32 v[138:139], v[138:139], v[144:145], v[38:39]
	v_pk_fma_f32 v[140:141], v[140:141], v[144:145], v[38:39]
	v_exp_f32_e32 v138, v138
	v_exp_f32_e32 v139, v139
	v_exp_f32_e32 v140, v140
	v_exp_f32_e32 v141, v141
	v_pk_add_f32 v[40:41], v[40:41], v[134:135]
	v_pk_add_f32 v[40:41], v[40:41], v[136:137]
	s_nop 0
	v_pk_add_f32 v[40:41], v[40:41], v[138:139]
	v_pk_add_f32 v[40:41], v[40:41], v[140:141]
	v_add_f32_e32 v36, v40, v41
	v_mov_b32_e32 v37, v36
	s_nop 1
	v_permlane16_swap_b32_e32 v36, v37
	v_add_f32_e32 v36, v36, v37
	v_mov_b32_e32 v37, v36
	s_nop 1
	v_permlane32_swap_b32_e32 v36, v37
	v_add_f32_e32 v36, v36, v37
	v_rcp_f32_e32 v142, v36
	v_cvt_pk_bf16_f32 v78, v78, v79
	v_cvt_pk_bf16_f32 v79, v80, v81
	v_cvt_pk_bf16_f32 v80, v82, v83
	v_cvt_pk_bf16_f32 v81, v84, v85
	v_cvt_pk_bf16_f32 v86, v86, v87
	v_cvt_pk_bf16_f32 v87, v88, v89
	v_cvt_pk_bf16_f32 v88, v90, v91
	v_cvt_pk_bf16_f32 v89, v92, v93
	v_cvt_pk_bf16_f32 v94, v94, v95
	v_cvt_pk_bf16_f32 v95, v96, v97
	v_cvt_pk_bf16_f32 v96, v98, v99
	v_cvt_pk_bf16_f32 v97, v100, v101
	v_cvt_pk_bf16_f32 v102, v102, v103
	v_cvt_pk_bf16_f32 v103, v104, v105
	v_cvt_pk_bf16_f32 v104, v106, v107
	v_cvt_pk_bf16_f32 v105, v108, v109
	v_cvt_pk_bf16_f32 v110, v110, v111
	v_cvt_pk_bf16_f32 v111, v112, v113
	v_cvt_pk_bf16_f32 v112, v114, v115
	v_cvt_pk_bf16_f32 v113, v116, v117
	v_cvt_pk_bf16_f32 v118, v118, v119
	v_cvt_pk_bf16_f32 v119, v120, v121
	v_cvt_pk_bf16_f32 v120, v122, v123
	v_cvt_pk_bf16_f32 v121, v124, v125
	v_cvt_pk_bf16_f32 v126, v126, v127
	v_cvt_pk_bf16_f32 v127, v128, v129
	v_cvt_pk_bf16_f32 v128, v130, v131
	v_cvt_pk_bf16_f32 v129, v132, v133
	v_cvt_pk_bf16_f32 v134, v134, v135
	v_cvt_pk_bf16_f32 v135, v136, v137
	v_cvt_pk_bf16_f32 v136, v138, v139
	v_cvt_pk_bf16_f32 v137, v140, v141
	v_fma_f32 v143, -v36, v142, 1.0
	v_fma_f32 v142, v143, v142, v142
	v_mov_b32_e32 v143, v142
	ds_read_b64 v[82:83], v73 offset:53824
	ds_read_b64 v[84:85], v73 offset:53856
	s_waitcnt lgkmcnt(12)
	v_mfma_f32_16x16x32_bf16 v[32:35], v[48:51], v[78:81], 0
	ds_read_b64 v[90:91], v73 offset:62272
	ds_read_b64 v[92:93], v73 offset:62304
	s_waitcnt lgkmcnt(12)
	v_mfma_f32_16x16x32_bf16 v[36:39], v[52:55], v[78:81], 0
	ds_read_b64 v[48:49], v73 offset:36992
	ds_read_b64 v[50:51], v73 offset:37024
	s_waitcnt lgkmcnt(12)
	v_mfma_f32_16x16x32_bf16 v[40:43], v[56:59], v[78:81], 0
	ds_read_b64 v[52:53], v73 offset:45440
	ds_read_b64 v[54:55], v73 offset:45472
	s_waitcnt lgkmcnt(12)
	v_mfma_f32_16x16x32_bf16 v[44:47], v[60:63], v[78:81], 0
	ds_read_b64 v[56:57], v73 offset:53888
	ds_read_b64 v[58:59], v73 offset:53920
	s_waitcnt lgkmcnt(12)
	v_mfma_f32_16x16x32_bf16 v[32:35], v[64:67], v[86:89], v[32:35]
	ds_read_b64 v[60:61], v73 offset:62336
	ds_read_b64 v[62:63], v73 offset:62368
	s_waitcnt lgkmcnt(12)
	v_mfma_f32_16x16x32_bf16 v[36:39], v[68:71], v[86:89], v[36:39]
	ds_read_b64 v[64:65], v73 offset:37056
	ds_read_b64 v[66:67], v73 offset:37088
	s_waitcnt lgkmcnt(12)
	v_mfma_f32_16x16x32_bf16 v[40:43], v[82:85], v[86:89], v[40:43]
	ds_read_b64 v[68:69], v73 offset:45504
	ds_read_b64 v[70:71], v73 offset:45536
	s_waitcnt lgkmcnt(12)
	v_mfma_f32_16x16x32_bf16 v[44:47], v[90:93], v[86:89], v[44:47]
	ds_read_b64 v[82:83], v73 offset:53952
	ds_read_b64 v[84:85], v73 offset:53984
	s_waitcnt lgkmcnt(12)
	v_mfma_f32_16x16x32_bf16 v[32:35], v[48:51], v[94:97], v[32:35]
	ds_read_b64 v[90:91], v73 offset:62400
	ds_read_b64 v[92:93], v73 offset:62432
	s_waitcnt lgkmcnt(12)
	v_mfma_f32_16x16x32_bf16 v[36:39], v[52:55], v[94:97], v[36:39]
	ds_read_b64 v[48:49], v73 offset:37120
	ds_read_b64 v[50:51], v73 offset:37152
	s_waitcnt lgkmcnt(12)
	v_mfma_f32_16x16x32_bf16 v[40:43], v[56:59], v[94:97], v[40:43]
	ds_read_b64 v[52:53], v73 offset:45568
	ds_read_b64 v[54:55], v73 offset:45600
	s_waitcnt lgkmcnt(12)
	v_mfma_f32_16x16x32_bf16 v[44:47], v[60:63], v[94:97], v[44:47]
	ds_read_b64 v[56:57], v73 offset:54016
	ds_read_b64 v[58:59], v73 offset:54048
	s_waitcnt lgkmcnt(12)
	v_mfma_f32_16x16x32_bf16 v[32:35], v[64:67], v[102:105], v[32:35]
	ds_read_b64 v[60:61], v73 offset:62464
	ds_read_b64 v[62:63], v73 offset:62496
	s_waitcnt lgkmcnt(12)
	v_mfma_f32_16x16x32_bf16 v[36:39], v[68:71], v[102:105], v[36:39]
	ds_read_b64 v[64:65], v73 offset:37184
	ds_read_b64 v[66:67], v73 offset:37216
	s_waitcnt lgkmcnt(12)
	v_mfma_f32_16x16x32_bf16 v[40:43], v[82:85], v[102:105], v[40:43]
	ds_read_b64 v[68:69], v73 offset:45632
	ds_read_b64 v[70:71], v73 offset:45664
	s_waitcnt lgkmcnt(12)
	v_mfma_f32_16x16x32_bf16 v[44:47], v[90:93], v[102:105], v[44:47]
	ds_read_b64 v[82:83], v73 offset:54080
	ds_read_b64 v[84:85], v73 offset:54112
	s_waitcnt lgkmcnt(12)
	v_mfma_f32_16x16x32_bf16 v[32:35], v[48:51], v[110:113], v[32:35]
	ds_read_b64 v[90:91], v73 offset:62528
	ds_read_b64 v[92:93], v73 offset:62560
	s_waitcnt lgkmcnt(12)
	v_mfma_f32_16x16x32_bf16 v[36:39], v[52:55], v[110:113], v[36:39]
	ds_read_b64 v[48:49], v73 offset:37248
	ds_read_b64 v[50:51], v73 offset:37280
	s_waitcnt lgkmcnt(12)
	v_mfma_f32_16x16x32_bf16 v[40:43], v[56:59], v[110:113], v[40:43]
	ds_read_b64 v[52:53], v73 offset:45696
	ds_read_b64 v[54:55], v73 offset:45728
	s_waitcnt lgkmcnt(12)
	v_mfma_f32_16x16x32_bf16 v[44:47], v[60:63], v[110:113], v[44:47]
	ds_read_b64 v[56:57], v73 offset:54144
	ds_read_b64 v[58:59], v73 offset:54176
	s_waitcnt lgkmcnt(12)
	v_mfma_f32_16x16x32_bf16 v[32:35], v[64:67], v[118:121], v[32:35]
	ds_read_b64 v[60:61], v73 offset:62592
	ds_read_b64 v[62:63], v73 offset:62624
	s_waitcnt lgkmcnt(12)
	v_mfma_f32_16x16x32_bf16 v[36:39], v[68:71], v[118:121], v[36:39]
	ds_read_b64 v[64:65], v73 offset:37312
	ds_read_b64 v[66:67], v73 offset:37344
	s_waitcnt lgkmcnt(12)
	v_mfma_f32_16x16x32_bf16 v[40:43], v[82:85], v[118:121], v[40:43]
	ds_read_b64 v[68:69], v73 offset:45760
	ds_read_b64 v[70:71], v73 offset:45792
	s_waitcnt lgkmcnt(12)
	v_mfma_f32_16x16x32_bf16 v[44:47], v[90:93], v[118:121], v[44:47]
	ds_read_b64 v[82:83], v73 offset:54208
	ds_read_b64 v[84:85], v73 offset:54240
	s_waitcnt lgkmcnt(12)
	v_mfma_f32_16x16x32_bf16 v[32:35], v[48:51], v[126:129], v[32:35]
	ds_read_b64 v[90:91], v73 offset:62656
	ds_read_b64 v[92:93], v73 offset:62688
	s_waitcnt lgkmcnt(12)
	v_mfma_f32_16x16x32_bf16 v[36:39], v[52:55], v[126:129], v[36:39]
	s_waitcnt lgkmcnt(10)
	v_mfma_f32_16x16x32_bf16 v[40:43], v[56:59], v[126:129], v[40:43]
	s_waitcnt lgkmcnt(8)
	v_mfma_f32_16x16x32_bf16 v[44:47], v[60:63], v[126:129], v[44:47]
	s_waitcnt lgkmcnt(6)
	v_mfma_f32_16x16x32_bf16 v[32:35], v[64:67], v[134:137], v[32:35]
	s_waitcnt lgkmcnt(4)
	v_mfma_f32_16x16x32_bf16 v[36:39], v[68:71], v[134:137], v[36:39]
	s_waitcnt lgkmcnt(2)
	v_mfma_f32_16x16x32_bf16 v[40:43], v[82:85], v[134:137], v[40:43]
	s_waitcnt lgkmcnt(0)
	v_mfma_f32_16x16x32_bf16 v[44:47], v[90:93], v[134:137], v[44:47]
	ds_read_b128 v[48:51], v72 offset:0
	ds_read_b128 v[52:55], v146 offset:0
	ds_read_b128 v[56:59], v72 offset:2048
	ds_read_b128 v[60:63], v146 offset:2048
	ds_read_b128 v[64:67], v72 offset:4096
	ds_read_b128 v[68:71], v146 offset:4096
	s_add_u32 s16, s12, 0x80000
	s_addc_u32 s17, s13, 0
	s_nop 7
	v_pk_mul_f32 v[32:33], v[32:33], v[142:143]
	v_pk_mul_f32 v[34:35], v[34:35], v[142:143]
	v_pk_mul_f32 v[36:37], v[36:37], v[142:143]
	v_pk_mul_f32 v[38:39], v[38:39], v[142:143]
	v_pk_mul_f32 v[40:41], v[40:41], v[142:143]
	v_pk_mul_f32 v[42:43], v[42:43], v[142:143]
	v_pk_mul_f32 v[44:45], v[44:45], v[142:143]
	v_pk_mul_f32 v[46:47], v[46:47], v[142:143]
	v_cvt_pk_bf16_f32 v32, v32, v33
	v_cvt_pk_bf16_f32 v33, v34, v35
	v_cvt_pk_bf16_f32 v36, v36, v37
	v_cvt_pk_bf16_f32 v37, v38, v39
	v_cvt_pk_bf16_f32 v40, v40, v41
	v_cvt_pk_bf16_f32 v41, v42, v43
	v_cvt_pk_bf16_f32 v44, v44, v45
	v_cvt_pk_bf16_f32 v45, v46, v47
	global_store_dwordx2 v74, v[32:33], s[16:17] offset:0
	global_store_dwordx2 v74, v[36:37], s[16:17] offset:32
	global_store_dwordx2 v74, v[40:41], s[16:17] offset:64
	global_store_dwordx2 v74, v[44:45], s[16:17] offset:96
	ds_read_b128 v[32:35], v72 offset:6144
	ds_read_b128 v[36:39], v146 offset:6144
	ds_read_b128 v[40:43], v72 offset:8192
	s_waitcnt lgkmcnt(8)
	v_mfma_f32_16x16x32_bf16 v[78:81], v[48:51], v[24:27], 0
	ds_read_b128 v[44:47], v146 offset:8192
	s_waitcnt lgkmcnt(8)
	v_mfma_f32_16x16x32_bf16 v[78:81], v[52:55], v[28:31], v[78:81]
	ds_read_b128 v[48:51], v72 offset:10240
	s_waitcnt lgkmcnt(8)
	v_mfma_f32_16x16x32_bf16 v[82:85], v[56:59], v[24:27], 0
	ds_read_b128 v[52:55], v146 offset:10240
	s_waitcnt lgkmcnt(8)
	v_mfma_f32_16x16x32_bf16 v[82:85], v[60:63], v[28:31], v[82:85]
	ds_read_b128 v[56:59], v72 offset:12288
	s_waitcnt lgkmcnt(8)
	v_mfma_f32_16x16x32_bf16 v[86:89], v[64:67], v[24:27], 0
	ds_read_b128 v[60:63], v146 offset:12288
	s_waitcnt lgkmcnt(8)
	v_mfma_f32_16x16x32_bf16 v[86:89], v[68:71], v[28:31], v[86:89]
	ds_read_b128 v[64:67], v72 offset:14336
	s_waitcnt lgkmcnt(8)
	v_mfma_f32_16x16x32_bf16 v[90:93], v[32:35], v[24:27], 0
	ds_read_b128 v[68:71], v146 offset:14336
	s_waitcnt lgkmcnt(8)
	v_mfma_f32_16x16x32_bf16 v[90:93], v[36:39], v[28:31], v[90:93]
	ds_read_b128 v[32:35], v72 offset:16384
	s_waitcnt lgkmcnt(8)
	v_mfma_f32_16x16x32_bf16 v[94:97], v[40:43], v[24:27], 0
	ds_read_b128 v[36:39], v146 offset:16384
	s_waitcnt lgkmcnt(8)
	v_mfma_f32_16x16x32_bf16 v[94:97], v[44:47], v[28:31], v[94:97]
	ds_read_b128 v[40:43], v72 offset:18432
	s_waitcnt lgkmcnt(8)
	v_mfma_f32_16x16x32_bf16 v[98:101], v[48:51], v[24:27], 0
	ds_read_b128 v[44:47], v146 offset:18432
	s_waitcnt lgkmcnt(8)
	v_mfma_f32_16x16x32_bf16 v[98:101], v[52:55], v[28:31], v[98:101]
	ds_read_b128 v[48:51], v72 offset:20480
	s_waitcnt lgkmcnt(8)
	v_mfma_f32_16x16x32_bf16 v[102:105], v[56:59], v[24:27], 0
	ds_read_b128 v[52:55], v146 offset:20480
	s_waitcnt lgkmcnt(8)
	v_mfma_f32_16x16x32_bf16 v[102:105], v[60:63], v[28:31], v[102:105]
	ds_read_b128 v[56:59], v72 offset:22528
	s_waitcnt lgkmcnt(8)
	v_mfma_f32_16x16x32_bf16 v[106:109], v[64:67], v[24:27], 0
	ds_read_b128 v[60:63], v146 offset:22528
	s_waitcnt lgkmcnt(8)
	v_mfma_f32_16x16x32_bf16 v[106:109], v[68:71], v[28:31], v[106:109]
	ds_read_b128 v[64:67], v72 offset:24576
	s_waitcnt lgkmcnt(8)
	v_mfma_f32_16x16x32_bf16 v[110:113], v[32:35], v[24:27], 0
	ds_read_b128 v[68:71], v146 offset:24576
	s_waitcnt lgkmcnt(8)
	v_mfma_f32_16x16x32_bf16 v[110:113], v[36:39], v[28:31], v[110:113]
	ds_read_b128 v[32:35], v72 offset:26624
	s_waitcnt lgkmcnt(8)
	v_mfma_f32_16x16x32_bf16 v[114:117], v[40:43], v[24:27], 0
	ds_read_b128 v[36:39], v146 offset:26624
	s_waitcnt lgkmcnt(8)
	v_mfma_f32_16x16x32_bf16 v[114:117], v[44:47], v[28:31], v[114:117]
	ds_read_b128 v[40:43], v72 offset:28672
	s_waitcnt lgkmcnt(8)
	v_mfma_f32_16x16x32_bf16 v[118:121], v[48:51], v[24:27], 0
	ds_read_b128 v[44:47], v146 offset:28672
	s_waitcnt lgkmcnt(8)
	v_mfma_f32_16x16x32_bf16 v[118:121], v[52:55], v[28:31], v[118:121]
	ds_read_b128 v[48:51], v72 offset:30720
	s_waitcnt lgkmcnt(8)
	v_mfma_f32_16x16x32_bf16 v[122:125], v[56:59], v[24:27], 0
	ds_read_b128 v[52:55], v146 offset:30720
	s_waitcnt lgkmcnt(8)
	v_mfma_f32_16x16x32_bf16 v[122:125], v[60:63], v[28:31], v[122:125]
	s_waitcnt lgkmcnt(7)
	v_mfma_f32_16x16x32_bf16 v[126:129], v[64:67], v[24:27], 0
	s_waitcnt lgkmcnt(6)
	v_mfma_f32_16x16x32_bf16 v[126:129], v[68:71], v[28:31], v[126:129]
	s_waitcnt lgkmcnt(5)
	v_mfma_f32_16x16x32_bf16 v[130:133], v[32:35], v[24:27], 0
	s_waitcnt lgkmcnt(4)
	v_mfma_f32_16x16x32_bf16 v[130:133], v[36:39], v[28:31], v[130:133]
	s_waitcnt lgkmcnt(3)
	v_mfma_f32_16x16x32_bf16 v[134:137], v[40:43], v[24:27], 0
	s_waitcnt lgkmcnt(2)
	v_mfma_f32_16x16x32_bf16 v[134:137], v[44:47], v[28:31], v[134:137]
	s_waitcnt lgkmcnt(1)
	v_mfma_f32_16x16x32_bf16 v[138:141], v[48:51], v[24:27], 0
	s_waitcnt lgkmcnt(0)
	v_mfma_f32_16x16x32_bf16 v[138:141], v[52:55], v[28:31], v[138:141]
	ds_read_b64 v[48:49], v73 offset:36864
	ds_read_b64 v[50:51], v73 offset:36896
	ds_read_b64 v[52:53], v73 offset:45312
	ds_read_b64 v[54:55], v73 offset:45344
	ds_read_b64 v[56:57], v73 offset:53760
	ds_read_b64 v[58:59], v73 offset:53792
	ds_read_b64 v[60:61], v73 offset:62208
	ds_read_b64 v[62:63], v73 offset:62240
	ds_read_b64 v[64:65], v73 offset:36928
	ds_read_b64 v[66:67], v73 offset:36960
	ds_read_b64 v[68:69], v73 offset:45376
	ds_read_b64 v[70:71], v73 offset:45408
	v_max3_f32 v36, v78, v79, v80
	v_max3_f32 v36, v36, v81, v82
	v_max3_f32 v36, v36, v83, v84
	v_max3_f32 v36, v36, v85, v86
	v_max3_f32 v36, v36, v87, v88
	v_max3_f32 v36, v36, v89, v90
	v_max3_f32 v36, v36, v91, v92
	v_max3_f32 v36, v36, v93, v94
	v_max3_f32 v36, v36, v95, v96
	v_max3_f32 v36, v36, v97, v98
	v_max3_f32 v36, v36, v99, v100
	v_max3_f32 v36, v36, v101, v102
	v_max3_f32 v36, v36, v103, v104
	v_max3_f32 v36, v36, v105, v106
	v_max3_f32 v36, v36, v107, v108
	v_max3_f32 v36, v36, v109, v110
	v_max3_f32 v36, v36, v111, v112
	v_max3_f32 v36, v36, v113, v114
	v_max3_f32 v36, v36, v115, v116
	v_max3_f32 v36, v36, v117, v118
	v_max3_f32 v36, v36, v119, v120
	v_max3_f32 v36, v36, v121, v122
	v_max3_f32 v36, v36, v123, v124
	v_max3_f32 v36, v36, v125, v126
	v_max3_f32 v36, v36, v127, v128
	v_max3_f32 v36, v36, v129, v130
	v_max3_f32 v36, v36, v131, v132
	v_max3_f32 v36, v36, v133, v134
	v_max3_f32 v36, v36, v135, v136
	v_max3_f32 v36, v36, v137, v138
	v_max3_f32 v36, v36, v139, v140
	v_max_f32_e32 v36, v36, v141
	v_mov_b32_e32 v37, v36
	s_nop 1
	v_permlane16_swap_b32_e32 v36, v37
	v_max_f32_e32 v36, v36, v37
	v_mov_b32_e32 v37, v36
	s_nop 1
	v_permlane32_swap_b32_e32 v36, v37
	v_max_f32_e32 v36, v36, v37
	v_mul_f32_e64 v38, v36, -v144
	v_mov_b32_e32 v40, 0
	v_mov_b32_e32 v41, 0
	v_mov_b32_e32 v39, v38
	v_pk_fma_f32 v[78:79], v[78:79], v[144:145], v[38:39]
	v_pk_fma_f32 v[80:81], v[80:81], v[144:145], v[38:39]
	v_exp_f32_e32 v78, v78
	v_exp_f32_e32 v79, v79
	v_exp_f32_e32 v80, v80
	v_exp_f32_e32 v81, v81
	v_pk_fma_f32 v[82:83], v[82:83], v[144:145], v[38:39]
	v_pk_fma_f32 v[84:85], v[84:85], v[144:145], v[38:39]
	v_exp_f32_e32 v82, v82
	v_exp_f32_e32 v83, v83
	v_exp_f32_e32 v84, v84
	v_exp_f32_e32 v85, v85
	v_pk_add_f32 v[40:41], v[40:41], v[78:79]
	v_pk_add_f32 v[40:41], v[40:41], v[80:81]
	v_pk_fma_f32 v[86:87], v[86:87], v[144:145], v[38:39]
	v_pk_fma_f32 v[88:89], v[88:89], v[144:145], v[38:39]
	v_exp_f32_e32 v86, v86
	v_exp_f32_e32 v87, v87
	v_exp_f32_e32 v88, v88
	v_exp_f32_e32 v89, v89
	v_pk_add_f32 v[40:41], v[40:41], v[82:83]
	v_pk_add_f32 v[40:41], v[40:41], v[84:85]
	v_pk_fma_f32 v[90:91], v[90:91], v[144:145], v[38:39]
	v_pk_fma_f32 v[92:93], v[92:93], v[144:145], v[38:39]
	v_exp_f32_e32 v90, v90
	v_exp_f32_e32 v91, v91
	v_exp_f32_e32 v92, v92
	v_exp_f32_e32 v93, v93
	v_pk_add_f32 v[40:41], v[40:41], v[86:87]
	v_pk_add_f32 v[40:41], v[40:41], v[88:89]
	v_pk_fma_f32 v[94:95], v[94:95], v[144:145], v[38:39]
	v_pk_fma_f32 v[96:97], v[96:97], v[144:145], v[38:39]
	v_exp_f32_e32 v94, v94
	v_exp_f32_e32 v95, v95
	v_exp_f32_e32 v96, v96
	v_exp_f32_e32 v97, v97
	v_pk_add_f32 v[40:41], v[40:41], v[90:91]
	v_pk_add_f32 v[40:41], v[40:41], v[92:93]
	v_pk_fma_f32 v[98:99], v[98:99], v[144:145], v[38:39]
	v_pk_fma_f32 v[100:101], v[100:101], v[144:145], v[38:39]
	v_exp_f32_e32 v98, v98
	v_exp_f32_e32 v99, v99
	v_exp_f32_e32 v100, v100
	v_exp_f32_e32 v101, v101
	v_pk_add_f32 v[40:41], v[40:41], v[94:95]
	v_pk_add_f32 v[40:41], v[40:41], v[96:97]
	v_pk_fma_f32 v[102:103], v[102:103], v[144:145], v[38:39]
	v_pk_fma_f32 v[104:105], v[104:105], v[144:145], v[38:39]
	v_exp_f32_e32 v102, v102
	v_exp_f32_e32 v103, v103
	v_exp_f32_e32 v104, v104
	v_exp_f32_e32 v105, v105
	v_pk_add_f32 v[40:41], v[40:41], v[98:99]
	v_pk_add_f32 v[40:41], v[40:41], v[100:101]
	v_pk_fma_f32 v[106:107], v[106:107], v[144:145], v[38:39]
	v_pk_fma_f32 v[108:109], v[108:109], v[144:145], v[38:39]
	v_exp_f32_e32 v106, v106
	v_exp_f32_e32 v107, v107
	v_exp_f32_e32 v108, v108
	v_exp_f32_e32 v109, v109
	v_pk_add_f32 v[40:41], v[40:41], v[102:103]
	v_pk_add_f32 v[40:41], v[40:41], v[104:105]
	v_pk_fma_f32 v[110:111], v[110:111], v[144:145], v[38:39]
	v_pk_fma_f32 v[112:113], v[112:113], v[144:145], v[38:39]
	v_exp_f32_e32 v110, v110
	v_exp_f32_e32 v111, v111
	v_exp_f32_e32 v112, v112
	v_exp_f32_e32 v113, v113
	v_pk_add_f32 v[40:41], v[40:41], v[106:107]
	v_pk_add_f32 v[40:41], v[40:41], v[108:109]
	v_pk_fma_f32 v[114:115], v[114:115], v[144:145], v[38:39]
	v_pk_fma_f32 v[116:117], v[116:117], v[144:145], v[38:39]
	v_exp_f32_e32 v114, v114
	v_exp_f32_e32 v115, v115
	v_exp_f32_e32 v116, v116
	v_exp_f32_e32 v117, v117
	v_pk_add_f32 v[40:41], v[40:41], v[110:111]
	v_pk_add_f32 v[40:41], v[40:41], v[112:113]
	v_pk_fma_f32 v[118:119], v[118:119], v[144:145], v[38:39]
	v_pk_fma_f32 v[120:121], v[120:121], v[144:145], v[38:39]
	v_exp_f32_e32 v118, v118
	v_exp_f32_e32 v119, v119
	v_exp_f32_e32 v120, v120
	v_exp_f32_e32 v121, v121
	v_pk_add_f32 v[40:41], v[40:41], v[114:115]
	v_pk_add_f32 v[40:41], v[40:41], v[116:117]
	v_pk_fma_f32 v[122:123], v[122:123], v[144:145], v[38:39]
	v_pk_fma_f32 v[124:125], v[124:125], v[144:145], v[38:39]
	v_exp_f32_e32 v122, v122
	v_exp_f32_e32 v123, v123
	v_exp_f32_e32 v124, v124
	v_exp_f32_e32 v125, v125
	v_pk_add_f32 v[40:41], v[40:41], v[118:119]
	v_pk_add_f32 v[40:41], v[40:41], v[120:121]
	v_pk_fma_f32 v[126:127], v[126:127], v[144:145], v[38:39]
	v_pk_fma_f32 v[128:129], v[128:129], v[144:145], v[38:39]
	v_exp_f32_e32 v126, v126
	v_exp_f32_e32 v127, v127
	v_exp_f32_e32 v128, v128
	v_exp_f32_e32 v129, v129
	v_pk_add_f32 v[40:41], v[40:41], v[122:123]
	v_pk_add_f32 v[40:41], v[40:41], v[124:125]
	v_pk_fma_f32 v[130:131], v[130:131], v[144:145], v[38:39]
	v_pk_fma_f32 v[132:133], v[132:133], v[144:145], v[38:39]
	v_exp_f32_e32 v130, v130
	v_exp_f32_e32 v131, v131
	v_exp_f32_e32 v132, v132
	v_exp_f32_e32 v133, v133
	v_pk_add_f32 v[40:41], v[40:41], v[126:127]
	v_pk_add_f32 v[40:41], v[40:41], v[128:129]
	v_pk_fma_f32 v[134:135], v[134:135], v[144:145], v[38:39]
	v_pk_fma_f32 v[136:137], v[136:137], v[144:145], v[38:39]
	v_exp_f32_e32 v134, v134
	v_exp_f32_e32 v135, v135
	v_exp_f32_e32 v136, v136
	v_exp_f32_e32 v137, v137
	v_pk_add_f32 v[40:41], v[40:41], v[130:131]
	v_pk_add_f32 v[40:41], v[40:41], v[132:133]
	v_pk_fma_f32 v[138:139], v[138:139], v[144:145], v[38:39]
	v_pk_fma_f32 v[140:141], v[140:141], v[144:145], v[38:39]
	v_exp_f32_e32 v138, v138
	v_exp_f32_e32 v139, v139
	v_exp_f32_e32 v140, v140
	v_exp_f32_e32 v141, v141
	v_pk_add_f32 v[40:41], v[40:41], v[134:135]
	v_pk_add_f32 v[40:41], v[40:41], v[136:137]
	s_nop 0
	v_pk_add_f32 v[40:41], v[40:41], v[138:139]
	v_pk_add_f32 v[40:41], v[40:41], v[140:141]
	v_add_f32_e32 v36, v40, v41
	v_mov_b32_e32 v37, v36
	s_nop 1
	v_permlane16_swap_b32_e32 v36, v37
	v_add_f32_e32 v36, v36, v37
	v_mov_b32_e32 v37, v36
	s_nop 1
	v_permlane32_swap_b32_e32 v36, v37
	v_add_f32_e32 v36, v36, v37
	v_rcp_f32_e32 v142, v36
	v_cvt_pk_bf16_f32 v78, v78, v79
	v_cvt_pk_bf16_f32 v79, v80, v81
	v_cvt_pk_bf16_f32 v80, v82, v83
	v_cvt_pk_bf16_f32 v81, v84, v85
	v_cvt_pk_bf16_f32 v86, v86, v87
	v_cvt_pk_bf16_f32 v87, v88, v89
	v_cvt_pk_bf16_f32 v88, v90, v91
	v_cvt_pk_bf16_f32 v89, v92, v93
	v_cvt_pk_bf16_f32 v94, v94, v95
	v_cvt_pk_bf16_f32 v95, v96, v97
	v_cvt_pk_bf16_f32 v96, v98, v99
	v_cvt_pk_bf16_f32 v97, v100, v101
	v_cvt_pk_bf16_f32 v102, v102, v103
	v_cvt_pk_bf16_f32 v103, v104, v105
	v_cvt_pk_bf16_f32 v104, v106, v107
	v_cvt_pk_bf16_f32 v105, v108, v109
	v_cvt_pk_bf16_f32 v110, v110, v111
	v_cvt_pk_bf16_f32 v111, v112, v113
	v_cvt_pk_bf16_f32 v112, v114, v115
	v_cvt_pk_bf16_f32 v113, v116, v117
	v_cvt_pk_bf16_f32 v118, v118, v119
	v_cvt_pk_bf16_f32 v119, v120, v121
	v_cvt_pk_bf16_f32 v120, v122, v123
	v_cvt_pk_bf16_f32 v121, v124, v125
	v_cvt_pk_bf16_f32 v126, v126, v127
	v_cvt_pk_bf16_f32 v127, v128, v129
	v_cvt_pk_bf16_f32 v128, v130, v131
	v_cvt_pk_bf16_f32 v129, v132, v133
	v_cvt_pk_bf16_f32 v134, v134, v135
	v_cvt_pk_bf16_f32 v135, v136, v137
	v_cvt_pk_bf16_f32 v136, v138, v139
	v_cvt_pk_bf16_f32 v137, v140, v141
	v_fma_f32 v143, -v36, v142, 1.0
	v_fma_f32 v142, v143, v142, v142
	v_mov_b32_e32 v143, v142
	ds_read_b64 v[82:83], v73 offset:53824
	ds_read_b64 v[84:85], v73 offset:53856
	s_waitcnt lgkmcnt(12)
	v_mfma_f32_16x16x32_bf16 v[32:35], v[48:51], v[78:81], 0
	ds_read_b64 v[90:91], v73 offset:62272
	ds_read_b64 v[92:93], v73 offset:62304
	s_waitcnt lgkmcnt(12)
	v_mfma_f32_16x16x32_bf16 v[36:39], v[52:55], v[78:81], 0
	ds_read_b64 v[48:49], v73 offset:36992
	ds_read_b64 v[50:51], v73 offset:37024
	s_waitcnt lgkmcnt(12)
	v_mfma_f32_16x16x32_bf16 v[40:43], v[56:59], v[78:81], 0
	ds_read_b64 v[52:53], v73 offset:45440
	ds_read_b64 v[54:55], v73 offset:45472
	s_waitcnt lgkmcnt(12)
	v_mfma_f32_16x16x32_bf16 v[44:47], v[60:63], v[78:81], 0
	ds_read_b64 v[56:57], v73 offset:53888
	ds_read_b64 v[58:59], v73 offset:53920
	s_waitcnt lgkmcnt(12)
	v_mfma_f32_16x16x32_bf16 v[32:35], v[64:67], v[86:89], v[32:35]
	ds_read_b64 v[60:61], v73 offset:62336
	ds_read_b64 v[62:63], v73 offset:62368
	s_waitcnt lgkmcnt(12)
	v_mfma_f32_16x16x32_bf16 v[36:39], v[68:71], v[86:89], v[36:39]
	ds_read_b64 v[64:65], v73 offset:37056
	ds_read_b64 v[66:67], v73 offset:37088
	s_waitcnt lgkmcnt(12)
	v_mfma_f32_16x16x32_bf16 v[40:43], v[82:85], v[86:89], v[40:43]
	ds_read_b64 v[68:69], v73 offset:45504
	ds_read_b64 v[70:71], v73 offset:45536
	s_waitcnt lgkmcnt(12)
	v_mfma_f32_16x16x32_bf16 v[44:47], v[90:93], v[86:89], v[44:47]
	ds_read_b64 v[82:83], v73 offset:53952
	ds_read_b64 v[84:85], v73 offset:53984
	s_waitcnt lgkmcnt(12)
	v_mfma_f32_16x16x32_bf16 v[32:35], v[48:51], v[94:97], v[32:35]
	ds_read_b64 v[90:91], v73 offset:62400
	ds_read_b64 v[92:93], v73 offset:62432
	s_waitcnt lgkmcnt(12)
	v_mfma_f32_16x16x32_bf16 v[36:39], v[52:55], v[94:97], v[36:39]
	ds_read_b64 v[48:49], v73 offset:37120
	ds_read_b64 v[50:51], v73 offset:37152
	s_waitcnt lgkmcnt(12)
	v_mfma_f32_16x16x32_bf16 v[40:43], v[56:59], v[94:97], v[40:43]
	ds_read_b64 v[52:53], v73 offset:45568
	ds_read_b64 v[54:55], v73 offset:45600
	s_waitcnt lgkmcnt(12)
	v_mfma_f32_16x16x32_bf16 v[44:47], v[60:63], v[94:97], v[44:47]
	ds_read_b64 v[56:57], v73 offset:54016
	ds_read_b64 v[58:59], v73 offset:54048
	s_waitcnt lgkmcnt(12)
	v_mfma_f32_16x16x32_bf16 v[32:35], v[64:67], v[102:105], v[32:35]
	ds_read_b64 v[60:61], v73 offset:62464
	ds_read_b64 v[62:63], v73 offset:62496
	s_waitcnt lgkmcnt(12)
	v_mfma_f32_16x16x32_bf16 v[36:39], v[68:71], v[102:105], v[36:39]
	ds_read_b64 v[64:65], v73 offset:37184
	ds_read_b64 v[66:67], v73 offset:37216
	s_waitcnt lgkmcnt(12)
	v_mfma_f32_16x16x32_bf16 v[40:43], v[82:85], v[102:105], v[40:43]
	ds_read_b64 v[68:69], v73 offset:45632
	ds_read_b64 v[70:71], v73 offset:45664
	s_waitcnt lgkmcnt(12)
	v_mfma_f32_16x16x32_bf16 v[44:47], v[90:93], v[102:105], v[44:47]
	ds_read_b64 v[82:83], v73 offset:54080
	ds_read_b64 v[84:85], v73 offset:54112
	s_waitcnt lgkmcnt(12)
	v_mfma_f32_16x16x32_bf16 v[32:35], v[48:51], v[110:113], v[32:35]
	ds_read_b64 v[90:91], v73 offset:62528
	ds_read_b64 v[92:93], v73 offset:62560
	s_waitcnt lgkmcnt(12)
	v_mfma_f32_16x16x32_bf16 v[36:39], v[52:55], v[110:113], v[36:39]
	ds_read_b64 v[48:49], v73 offset:37248
	ds_read_b64 v[50:51], v73 offset:37280
	s_waitcnt lgkmcnt(12)
	v_mfma_f32_16x16x32_bf16 v[40:43], v[56:59], v[110:113], v[40:43]
	ds_read_b64 v[52:53], v73 offset:45696
	ds_read_b64 v[54:55], v73 offset:45728
	s_waitcnt lgkmcnt(12)
	v_mfma_f32_16x16x32_bf16 v[44:47], v[60:63], v[110:113], v[44:47]
	ds_read_b64 v[56:57], v73 offset:54144
	ds_read_b64 v[58:59], v73 offset:54176
	s_waitcnt lgkmcnt(12)
	v_mfma_f32_16x16x32_bf16 v[32:35], v[64:67], v[118:121], v[32:35]
	ds_read_b64 v[60:61], v73 offset:62592
	ds_read_b64 v[62:63], v73 offset:62624
	s_waitcnt lgkmcnt(12)
	v_mfma_f32_16x16x32_bf16 v[36:39], v[68:71], v[118:121], v[36:39]
	ds_read_b64 v[64:65], v73 offset:37312
	ds_read_b64 v[66:67], v73 offset:37344
	s_waitcnt lgkmcnt(12)
	v_mfma_f32_16x16x32_bf16 v[40:43], v[82:85], v[118:121], v[40:43]
	ds_read_b64 v[68:69], v73 offset:45760
	ds_read_b64 v[70:71], v73 offset:45792
	s_waitcnt lgkmcnt(12)
	v_mfma_f32_16x16x32_bf16 v[44:47], v[90:93], v[118:121], v[44:47]
	ds_read_b64 v[82:83], v73 offset:54208
	ds_read_b64 v[84:85], v73 offset:54240
	s_waitcnt lgkmcnt(12)
	v_mfma_f32_16x16x32_bf16 v[32:35], v[48:51], v[126:129], v[32:35]
	ds_read_b64 v[90:91], v73 offset:62656
	ds_read_b64 v[92:93], v73 offset:62688
	s_waitcnt lgkmcnt(12)
	v_mfma_f32_16x16x32_bf16 v[36:39], v[52:55], v[126:129], v[36:39]
	s_waitcnt lgkmcnt(10)
	v_mfma_f32_16x16x32_bf16 v[40:43], v[56:59], v[126:129], v[40:43]
	s_waitcnt lgkmcnt(8)
	v_mfma_f32_16x16x32_bf16 v[44:47], v[60:63], v[126:129], v[44:47]
	s_waitcnt lgkmcnt(6)
	v_mfma_f32_16x16x32_bf16 v[32:35], v[64:67], v[134:137], v[32:35]
	s_waitcnt lgkmcnt(4)
	v_mfma_f32_16x16x32_bf16 v[36:39], v[68:71], v[134:137], v[36:39]
	s_waitcnt lgkmcnt(2)
	v_mfma_f32_16x16x32_bf16 v[40:43], v[82:85], v[134:137], v[40:43]
	s_waitcnt lgkmcnt(0)
	v_mfma_f32_16x16x32_bf16 v[44:47], v[90:93], v[134:137], v[44:47]
	s_add_u32 s16, s12, 0x88000
	s_addc_u32 s17, s13, 0
	s_nop 7
	v_pk_mul_f32 v[32:33], v[32:33], v[142:143]
	v_pk_mul_f32 v[34:35], v[34:35], v[142:143]
	v_pk_mul_f32 v[36:37], v[36:37], v[142:143]
	v_pk_mul_f32 v[38:39], v[38:39], v[142:143]
	v_pk_mul_f32 v[40:41], v[40:41], v[142:143]
	v_pk_mul_f32 v[42:43], v[42:43], v[142:143]
	v_pk_mul_f32 v[44:45], v[44:45], v[142:143]
	v_pk_mul_f32 v[46:47], v[46:47], v[142:143]
	v_cvt_pk_bf16_f32 v32, v32, v33
	v_cvt_pk_bf16_f32 v33, v34, v35
	v_cvt_pk_bf16_f32 v36, v36, v37
	v_cvt_pk_bf16_f32 v37, v38, v39
	v_cvt_pk_bf16_f32 v40, v40, v41
	v_cvt_pk_bf16_f32 v41, v42, v43
	v_cvt_pk_bf16_f32 v44, v44, v45
	v_cvt_pk_bf16_f32 v45, v46, v47
	global_store_dwordx2 v74, v[32:33], s[16:17] offset:0
	global_store_dwordx2 v74, v[36:37], s[16:17] offset:32
	global_store_dwordx2 v74, v[40:41], s[16:17] offset:64
	global_store_dwordx2 v74, v[44:45], s[16:17] offset:96
	s_barrier
	s_branch .LBB0_270
